# v47 plus removal of the 16 redundant post-barrier lgkmcnt(0) waits in the four GEMM K-loops
# baseline (speedup 1.0000x reference)
; #define PG8_STAGE(bufoff, gbase, voff) do { _Pragma("unroll") for (int _i = 0; _i < 2; ++_i) \
;         __builtin_amdgcn_global_load_lds((const unsigned*)((const char*)(gbase) + (voff)[_i]), (PG8_LAS unsigned*)(lds + (bufoff) + ldsw + _i * 8192), 16, 0, 0); } while (0)
; #define PG8_LDA(dst, b, h) do { _Pragma("unroll") for (int m = 0; m < 4; ++m) _Pragma("unroll") for (int k = 0; k < 2; ++k) dst[m][k] = *(const PG8_LAS bf16x8*)(lds + PG8_SA(b, h) + aoff + m * 2048 + k * 1024); } while (0)
; #define PG8_LDB(dst, b, h) do { _Pragma("unroll") for (int n = 0; n < 2; ++n) _Pragma("unroll") for (int k = 0; k < 2; ++k) dst[n][k] = *(const PG8_LAS bf16x8*)(lds + PG8_SB(b, h) + boff + n * 2048 + k * 1024); } while (0)
; #define PG8_WAIT_V(n) asm volatile("s_waitcnt vmcnt(" #n ")" ::: "memory")
; #define PG8_WAIT_L(n) asm volatile("s_waitcnt lgkmcnt(" #n ")" ::: "memory")
; template <class Epi, class Sched, bool ALIGN_EPI = false, bool SP2 = false>
; __device__ __forceinline__ void gemm_phase(PG8_LAS unsigned char* lds, const Gemm g, const Sched& S, const Epi& E) {
;     ...
;     for (;;) {
;         const bool has_next = S.next(ui + 1, nxt);
;         const char* nA = has_next ? (const char*)g.A + (size_t)nxt.pm * tstep + (size_t)nxt.k0 * 2 : cA; const char* nB = has_next ? (const char*)g.Bt + (size_t)nxt.pn * tstep + (size_t)nxt.k0 * 2 : cB;
;         const int unt = cur.nt ? cur.nt : nt;
;         for (int t = 0; t < unt; t += 2) {
;             const bool last = (t == unt - 2);
;             const char* a1 = cA + (size_t)(t + 1) * kstep;
;             const char* a2 = last ? nA : cA + (size_t)(t + 2) * kstep; const char* b2 = last ? nB : cB + (size_t)(t + 2) * kstep;
;             const char* a3 = a2 + kstep; const char* b3 = b2 + kstep;
;             if (last && has_next) S.a_ready(nxt);
;             if constexpr (SP2) {
;             PG8_LDB(B0, 0, 0); PG8_LDB(B1, 0, 1); PG8_SCHED; PG8_LDA(At, 0, 0); PG8_STAGE(PG8_SA(1, 1), a1 + hstep, voffA);
;             PG8_WAIT_V(8); PG8_WAIT_L(0); PG8_BAR; PG8_MMA(0, 0, At, B0); PG8_MMA(0, 1, At, B1); PG8_BAR; PG8_SCHED;
;             PG8_LDA(At, 0, 1); PG8_STAGE(PG8_SB(0, 0), b2, voffB); PG8_STAGE(PG8_SB(0, 1), b2 + hstep, voffB); PG8_STAGE(PG8_SA(0, 0), a2, voffA);
;             PG8_WAIT_V(8); PG8_WAIT_L(0); PG8_BAR; PG8_MMA(1, 0, At, B0); PG8_MMA(1, 1, At, B1); PG8_BAR; PG8_SCHED;
.LBB0_197:
	s_add_u32 s6, s46, 0xfffc0080
	s_addc_u32 s7, s47, -1
	s_add_i32 s71, 0, 0x10000
	s_cmp_eq_u32 s70, 12
	s_cselect_b32 s51, s35, s7
	s_cselect_b32 s50, s66, s6
	s_cselect_b32 s49, s31, s69
	s_cselect_b32 s48, s67, s68
	s_add_i32 s6, 0, 0x14000
	v_add_u32_e32 v156, s71, v145
	v_add_u32_e32 v172, s6, v145
	ds_read_b128 v[140:143], v156
	ds_read_b128 v[148:151], v156 offset:1024
	ds_read_b128 v[152:155], v156 offset:2048
	ds_read_b128 v[156:159], v156 offset:3072
	ds_read_b128 v[160:163], v172
	ds_read_b128 v[164:167], v172 offset:1024
	ds_read_b128 v[168:171], v172 offset:2048
	ds_read_b128 v[172:175], v172 offset:3072
	s_add_i32 m0, s45, 0xc000
	ds_read_b128 v[176:179], v147
	ds_read_b128 v[180:183], v147 offset:1024
	ds_read_b128 v[184:187], v147 offset:2048
	ds_read_b128 v[188:191], v147 offset:3072
	ds_read_b128 v[192:195], v147 offset:4096
	ds_read_b128 v[196:199], v147 offset:5120
	ds_read_b128 v[200:203], v147 offset:6144
	ds_read_b128 v[212:215], v147 offset:7168
	global_load_lds_dwordx4 v136, s[46:47]
	s_add_i32 m0, s45, 0xe000
	s_nop 0
	global_load_lds_dwordx4 v138, s[46:47]
	s_waitcnt vmcnt(8)
	s_waitcnt lgkmcnt(0)
	s_barrier
	s_setprio 1
	v_mfma_f32_16x16x32_bf16 v[126:129], v[140:143], v[176:179], v[126:129]
	v_mfma_f32_16x16x32_bf16 v[122:125], v[152:155], v[176:179], v[122:125]
	v_mfma_f32_16x16x32_bf16 v[118:121], v[140:143], v[184:187], v[118:121]
	v_mfma_f32_16x16x32_bf16 v[110:113], v[152:155], v[184:187], v[110:113]
	v_mfma_f32_16x16x32_bf16 v[102:105], v[140:143], v[192:195], v[102:105]
	v_mfma_f32_16x16x32_bf16 v[94:97], v[152:155], v[192:195], v[94:97]
	v_mfma_f32_16x16x32_bf16 v[86:89], v[140:143], v[200:203], v[86:89]
	v_mfma_f32_16x16x32_bf16 v[78:81], v[152:155], v[200:203], v[78:81]
	v_mfma_f32_16x16x32_bf16 v[126:129], v[148:151], v[180:183], v[126:129]
	v_mfma_f32_16x16x32_bf16 v[122:125], v[156:159], v[180:183], v[122:125]
	v_mfma_f32_16x16x32_bf16 v[118:121], v[148:151], v[188:191], v[118:121]
	v_mfma_f32_16x16x32_bf16 v[110:113], v[156:159], v[188:191], v[110:113]
	v_mfma_f32_16x16x32_bf16 v[102:105], v[148:151], v[196:199], v[102:105]
	v_mfma_f32_16x16x32_bf16 v[94:97], v[156:159], v[196:199], v[94:97]
	v_mfma_f32_16x16x32_bf16 v[86:89], v[148:151], v[212:215], v[86:89]
	v_mfma_f32_16x16x32_bf16 v[78:81], v[156:159], v[212:215], v[78:81]
	s_setprio 0
	s_setprio 1
	v_mfma_f32_16x16x32_bf16 v[114:117], v[160:163], v[176:179], v[114:117]
	v_mfma_f32_16x16x32_bf16 v[106:109], v[168:171], v[176:179], v[106:109]
	v_mfma_f32_16x16x32_bf16 v[98:101], v[160:163], v[184:187], v[98:101]
	v_mfma_f32_16x16x32_bf16 v[90:93], v[168:171], v[184:187], v[90:93]
	v_mfma_f32_16x16x32_bf16 v[82:85], v[160:163], v[192:195], v[82:85]
	v_mfma_f32_16x16x32_bf16 v[74:77], v[168:171], v[192:195], v[74:77]
	v_mfma_f32_16x16x32_bf16 v[70:73], v[160:163], v[200:203], v[70:73]
	v_mfma_f32_16x16x32_bf16 v[66:69], v[168:171], v[200:203], v[66:69]
	v_mfma_f32_16x16x32_bf16 v[114:117], v[164:167], v[180:183], v[114:117]
	v_mfma_f32_16x16x32_bf16 v[106:109], v[172:175], v[180:183], v[106:109]
	v_mfma_f32_16x16x32_bf16 v[98:101], v[164:167], v[188:191], v[98:101]
	v_mfma_f32_16x16x32_bf16 v[90:93], v[172:175], v[188:191], v[90:93]
	v_mfma_f32_16x16x32_bf16 v[82:85], v[164:167], v[196:199], v[82:85]
	v_mfma_f32_16x16x32_bf16 v[74:77], v[172:175], v[196:199], v[74:77]
	v_mfma_f32_16x16x32_bf16 v[70:73], v[164:167], v[212:215], v[70:73]
	v_mfma_f32_16x16x32_bf16 v[66:69], v[172:175], v[212:215], v[66:69]
	s_setprio 0
	s_barrier
	s_add_i32 s7, s71, s60
	s_add_u32 s98, s48, s22
	s_addc_u32 s99, s49, s23
	s_mov_b32 m0, s7
	ds_read_b128 v[176:179], v147 offset:16384
	ds_read_b128 v[180:183], v147 offset:17408
	ds_read_b128 v[184:187], v147 offset:18432
	ds_read_b128 v[188:191], v147 offset:19456
	ds_read_b128 v[192:195], v147 offset:20480
	ds_read_b128 v[196:199], v147 offset:21504
	ds_read_b128 v[200:203], v147 offset:22528
	ds_read_b128 v[212:215], v147 offset:23552
	global_load_lds_dwordx4 v0, s[48:49]
	s_add_i32 m0, s7, 0x2000
	s_add_u32 s76, s48, 0x40000
	s_addc_u32 s77, s49, 0
	s_add_i32 s6, s6, s60
	global_load_lds_dwordx4 v134, s[48:49]
	s_mov_b32 m0, s6
	s_add_u32 s100, s50, s22
	s_addc_u32 s101, s51, s23
	global_load_lds_dwordx4 v0, s[76:77]
	s_add_i32 m0, s6, 0x2000
	s_nop 0
	global_load_lds_dwordx4 v134, s[76:77]
	s_mov_b32 m0, s45
	s_nop 0
	global_load_lds_dwordx4 v130, s[50:51]
	s_mov_b32 m0, s4
	s_nop 0
	global_load_lds_dwordx4 v132, s[50:51]
	s_waitcnt vmcnt(8)
	s_waitcnt lgkmcnt(0)
	s_barrier
	s_setprio 1
	v_mfma_f32_16x16x32_bf16 v[62:65], v[140:143], v[176:179], v[62:65]
	v_mfma_f32_16x16x32_bf16 v[58:61], v[152:155], v[176:179], v[58:61]
	v_mfma_f32_16x16x32_bf16 v[54:57], v[140:143], v[184:187], v[54:57]
	v_mfma_f32_16x16x32_bf16 v[46:49], v[152:155], v[184:187], v[46:49]
	v_mfma_f32_16x16x32_bf16 v[38:41], v[140:143], v[192:195], v[38:41]
	v_mfma_f32_16x16x32_bf16 v[30:33], v[152:155], v[192:195], v[30:33]
	v_mfma_f32_16x16x32_bf16 v[22:25], v[140:143], v[200:203], v[22:25]
	v_mfma_f32_16x16x32_bf16 v[14:17], v[152:155], v[200:203], v[14:17]
	v_mfma_f32_16x16x32_bf16 v[62:65], v[148:151], v[180:183], v[62:65]
	v_mfma_f32_16x16x32_bf16 v[58:61], v[156:159], v[180:183], v[58:61]
	v_mfma_f32_16x16x32_bf16 v[54:57], v[148:151], v[188:191], v[54:57]
	v_mfma_f32_16x16x32_bf16 v[46:49], v[156:159], v[188:191], v[46:49]
	v_mfma_f32_16x16x32_bf16 v[38:41], v[148:151], v[196:199], v[38:41]
	v_mfma_f32_16x16x32_bf16 v[30:33], v[156:159], v[196:199], v[30:33]
	v_mfma_f32_16x16x32_bf16 v[22:25], v[148:151], v[212:215], v[22:25]
	v_mfma_f32_16x16x32_bf16 v[14:17], v[156:159], v[212:215], v[14:17]
	s_setprio 0
	s_setprio 1
	v_mfma_f32_16x16x32_bf16 v[50:53], v[160:163], v[176:179], v[50:53]
	v_mfma_f32_16x16x32_bf16 v[42:45], v[168:171], v[176:179], v[42:45]
	v_mfma_f32_16x16x32_bf16 v[34:37], v[160:163], v[184:187], v[34:37]
	v_mfma_f32_16x16x32_bf16 v[26:29], v[168:171], v[184:187], v[26:29]
	v_mfma_f32_16x16x32_bf16 v[18:21], v[160:163], v[192:195], v[18:21]
	v_mfma_f32_16x16x32_bf16 v[10:13], v[168:171], v[192:195], v[10:13]
	v_mfma_f32_16x16x32_bf16 v[6:9], v[160:163], v[200:203], v[6:9]
	v_mfma_f32_16x16x32_bf16 v[2:5], v[168:171], v[200:203], v[2:5]
	v_mfma_f32_16x16x32_bf16 v[50:53], v[164:167], v[180:183], v[50:53]
	v_mfma_f32_16x16x32_bf16 v[42:45], v[172:175], v[180:183], v[42:45]
	v_mfma_f32_16x16x32_bf16 v[34:37], v[164:167], v[188:191], v[34:37]
	v_mfma_f32_16x16x32_bf16 v[26:29], v[172:175], v[188:191], v[26:29]
	v_mfma_f32_16x16x32_bf16 v[18:21], v[164:167], v[196:199], v[18:21]
	v_mfma_f32_16x16x32_bf16 v[10:13], v[172:175], v[196:199], v[10:13]
	v_mfma_f32_16x16x32_bf16 v[6:9], v[164:167], v[212:215], v[6:9]
	v_mfma_f32_16x16x32_bf16 v[2:5], v[172:175], v[212:215], v[2:5]
	s_setprio 0
	s_barrier
; #define PG8_STAGE(bufoff, gbase, voff) do { _Pragma("unroll") for (int _i = 0; _i < 2; ++_i) \
;         __builtin_amdgcn_global_load_lds((const unsigned*)((const char*)(gbase) + (voff)[_i]), (PG8_LAS unsigned*)(lds + (bufoff) + ldsw + _i * 8192), 16, 0, 0); } while (0)
; #define PG8_LDA(dst, b, h) do { _Pragma("unroll") for (int m = 0; m < 4; ++m) _Pragma("unroll") for (int k = 0; k < 2; ++k) dst[m][k] = *(const PG8_LAS bf16x8*)(lds + PG8_SA(b, h) + aoff + m * 2048 + k * 1024); } while (0)
; #define PG8_LDB(dst, b, h) do { _Pragma("unroll") for (int n = 0; n < 2; ++n) _Pragma("unroll") for (int k = 0; k < 2; ++k) dst[n][k] = *(const PG8_LAS bf16x8*)(lds + PG8_SB(b, h) + boff + n * 2048 + k * 1024); } while (0)
; template <class Epi, class Sched, bool ALIGN_EPI = false, bool SP2 = false>
; __device__ __forceinline__ void gemm_phase(PG8_LAS unsigned char* lds, const Gemm g, const Sched& S, const Epi& E) {
;     ...
;         for (int t = 0; t < unt; t += 2) {
;             const bool last = (t == unt - 2);
;             const char* a1 = cA + (size_t)(t + 1) * kstep;
;             const char* a2 = last ? nA : cA + (size_t)(t + 2) * kstep; const char* b2 = last ? nB : cB + (size_t)(t + 2) * kstep;
;             const char* a3 = a2 + kstep; const char* b3 = b2 + kstep;
;             if (last && has_next) S.a_ready(nxt);
;             if constexpr (SP2) {
;             PG8_LDB(B0, 0, 0); PG8_LDB(B1, 0, 1); PG8_SCHED; PG8_LDA(At, 0, 0); PG8_STAGE(PG8_SA(1, 1), a1 + hstep, voffA);
;             PG8_WAIT_V(8); PG8_WAIT_L(0); PG8_BAR; PG8_MMA(0, 0, At, B0); PG8_MMA(0, 1, At, B1); PG8_BAR; PG8_SCHED;
;             PG8_LDA(At, 0, 1); PG8_STAGE(PG8_SB(0, 0), b2, voffB); PG8_STAGE(PG8_SB(0, 1), b2 + hstep, voffB); PG8_STAGE(PG8_SA(0, 0), a2, voffA);
;             PG8_WAIT_V(8); PG8_WAIT_L(0); PG8_BAR; PG8_MMA(1, 0, At, B0); PG8_MMA(1, 1, At, B1); PG8_BAR; PG8_SCHED;
;             PG8_LDB(B0, 1, 0); PG8_LDB(B1, 1, 1); PG8_SCHED; PG8_LDA(At, 1, 0); PG8_STAGE(PG8_SA(0, 1), a2 + hstep, voffA);
;             PG8_WAIT_V(8); PG8_WAIT_L(0); PG8_BAR; PG8_MMA(0, 0, At, B0); PG8_MMA(0, 1, At, B1); PG8_BAR; PG8_SCHED;
;             PG8_LDA(At, 1, 1); PG8_STAGE(PG8_SB(1, 0), b3, voffB); PG8_STAGE(PG8_SB(1, 1), b3 + hstep, voffB); PG8_STAGE(PG8_SA(1, 0), a3, voffA);
;             PG8_WAIT_V(8); PG8_WAIT_L(0); PG8_BAR; PG8_MMA(1, 0, At, B0); PG8_MMA(1, 1, At, B1); PG8_BAR; PG8_SCHED;
	s_add_i32 s6, 0, 0x18000
	s_add_i32 s7, 0, 0x1c000
	v_add_u32_e32 v156, s6, v145
	v_add_u32_e32 v172, s7, v145
	ds_read_b128 v[140:143], v156
	ds_read_b128 v[148:151], v156 offset:1024
	ds_read_b128 v[152:155], v156 offset:2048
	ds_read_b128 v[156:159], v156 offset:3072
	ds_read_b128 v[160:163], v172
	ds_read_b128 v[164:167], v172 offset:1024
	ds_read_b128 v[168:171], v172 offset:2048
	ds_read_b128 v[172:175], v172 offset:3072
	s_add_u32 s50, s50, 0x40000
	s_addc_u32 s51, s51, 0
	s_mov_b32 m0, s5
	ds_read_b128 v[176:179], v147 offset:32768
	ds_read_b128 v[180:183], v147 offset:33792
	ds_read_b128 v[184:187], v147 offset:34816
	ds_read_b128 v[188:191], v147 offset:35840
	ds_read_b128 v[192:195], v147 offset:36864
	ds_read_b128 v[196:199], v147 offset:37888
	ds_read_b128 v[200:203], v147 offset:38912
	ds_read_b128 v[212:215], v147 offset:39936
	global_load_lds_dwordx4 v130, s[50:51]
	s_mov_b32 m0, s61
	s_nop 0
	global_load_lds_dwordx4 v132, s[50:51]
	s_waitcnt vmcnt(8)
	s_waitcnt lgkmcnt(0)
	s_barrier
	s_setprio 1
	v_mfma_f32_16x16x32_bf16 v[126:129], v[140:143], v[176:179], v[126:129]
	v_mfma_f32_16x16x32_bf16 v[122:125], v[152:155], v[176:179], v[122:125]
	v_mfma_f32_16x16x32_bf16 v[118:121], v[140:143], v[184:187], v[118:121]
	v_mfma_f32_16x16x32_bf16 v[110:113], v[152:155], v[184:187], v[110:113]
	v_mfma_f32_16x16x32_bf16 v[102:105], v[140:143], v[192:195], v[102:105]
	v_mfma_f32_16x16x32_bf16 v[94:97], v[152:155], v[192:195], v[94:97]
	v_mfma_f32_16x16x32_bf16 v[86:89], v[140:143], v[200:203], v[86:89]
	v_mfma_f32_16x16x32_bf16 v[78:81], v[152:155], v[200:203], v[78:81]
	v_mfma_f32_16x16x32_bf16 v[126:129], v[148:151], v[180:183], v[126:129]
	v_mfma_f32_16x16x32_bf16 v[122:125], v[156:159], v[180:183], v[122:125]
	v_mfma_f32_16x16x32_bf16 v[118:121], v[148:151], v[188:191], v[118:121]
	v_mfma_f32_16x16x32_bf16 v[110:113], v[156:159], v[188:191], v[110:113]
	v_mfma_f32_16x16x32_bf16 v[102:105], v[148:151], v[196:199], v[102:105]
	v_mfma_f32_16x16x32_bf16 v[94:97], v[156:159], v[196:199], v[94:97]
	v_mfma_f32_16x16x32_bf16 v[86:89], v[148:151], v[212:215], v[86:89]
	v_mfma_f32_16x16x32_bf16 v[78:81], v[156:159], v[212:215], v[78:81]
	s_setprio 0
	s_setprio 1
	v_mfma_f32_16x16x32_bf16 v[114:117], v[160:163], v[176:179], v[114:117]
	v_mfma_f32_16x16x32_bf16 v[106:109], v[168:171], v[176:179], v[106:109]
	v_mfma_f32_16x16x32_bf16 v[98:101], v[160:163], v[184:187], v[98:101]
	v_mfma_f32_16x16x32_bf16 v[90:93], v[168:171], v[184:187], v[90:93]
	v_mfma_f32_16x16x32_bf16 v[82:85], v[160:163], v[192:195], v[82:85]
	v_mfma_f32_16x16x32_bf16 v[74:77], v[168:171], v[192:195], v[74:77]
	v_mfma_f32_16x16x32_bf16 v[70:73], v[160:163], v[200:203], v[70:73]
	v_mfma_f32_16x16x32_bf16 v[66:69], v[168:171], v[200:203], v[66:69]
	v_mfma_f32_16x16x32_bf16 v[114:117], v[164:167], v[180:183], v[114:117]
	v_mfma_f32_16x16x32_bf16 v[106:109], v[172:175], v[180:183], v[106:109]
	v_mfma_f32_16x16x32_bf16 v[98:101], v[164:167], v[188:191], v[98:101]
	v_mfma_f32_16x16x32_bf16 v[90:93], v[172:175], v[188:191], v[90:93]
	v_mfma_f32_16x16x32_bf16 v[82:85], v[164:167], v[196:199], v[82:85]
	v_mfma_f32_16x16x32_bf16 v[74:77], v[172:175], v[196:199], v[74:77]
	v_mfma_f32_16x16x32_bf16 v[70:73], v[164:167], v[212:215], v[70:73]
	v_mfma_f32_16x16x32_bf16 v[66:69], v[172:175], v[212:215], v[66:69]
	s_setprio 0
	s_barrier
	s_add_i32 s6, s6, s60
	s_mov_b32 m0, s6
	ds_read_b128 v[176:179], v147 offset:49152
	ds_read_b128 v[180:183], v147 offset:50176
	ds_read_b128 v[184:187], v147 offset:51200
	ds_read_b128 v[188:191], v147 offset:52224
	ds_read_b128 v[192:195], v147 offset:53248
	ds_read_b128 v[196:199], v147 offset:54272
	ds_read_b128 v[200:203], v147 offset:55296
	ds_read_b128 v[212:215], v147 offset:56320
	global_load_lds_dwordx4 v0, s[98:99]
	s_add_i32 m0, s6, 0x2000
	s_add_u32 s48, s48, 0x40080
	s_addc_u32 s49, s49, 0
	s_add_i32 s6, s7, s60
	global_load_lds_dwordx4 v134, s[98:99]
	s_mov_b32 m0, s6
	s_nop 0
	global_load_lds_dwordx4 v0, s[48:49]
	s_add_i32 m0, s6, 0x2000
	s_nop 0
	global_load_lds_dwordx4 v134, s[48:49]
	s_mov_b32 m0, s62
	s_nop 0
	global_load_lds_dwordx4 v130, s[100:101]
	s_mov_b32 m0, s63
	s_nop 0
	global_load_lds_dwordx4 v132, s[100:101]
	s_waitcnt vmcnt(8)
	s_waitcnt lgkmcnt(0)
	s_barrier
	s_setprio 1
	v_mfma_f32_16x16x32_bf16 v[62:65], v[140:143], v[176:179], v[62:65]
	v_mfma_f32_16x16x32_bf16 v[58:61], v[152:155], v[176:179], v[58:61]
	v_mfma_f32_16x16x32_bf16 v[54:57], v[140:143], v[184:187], v[54:57]
	v_mfma_f32_16x16x32_bf16 v[46:49], v[152:155], v[184:187], v[46:49]
	v_mfma_f32_16x16x32_bf16 v[38:41], v[140:143], v[192:195], v[38:41]
	v_mfma_f32_16x16x32_bf16 v[30:33], v[152:155], v[192:195], v[30:33]
	v_mfma_f32_16x16x32_bf16 v[22:25], v[140:143], v[200:203], v[22:25]
	v_mfma_f32_16x16x32_bf16 v[14:17], v[152:155], v[200:203], v[14:17]
	v_mfma_f32_16x16x32_bf16 v[62:65], v[148:151], v[180:183], v[62:65]
	v_mfma_f32_16x16x32_bf16 v[58:61], v[156:159], v[180:183], v[58:61]
	v_mfma_f32_16x16x32_bf16 v[54:57], v[148:151], v[188:191], v[54:57]
	v_mfma_f32_16x16x32_bf16 v[46:49], v[156:159], v[188:191], v[46:49]
	v_mfma_f32_16x16x32_bf16 v[38:41], v[148:151], v[196:199], v[38:41]
	v_mfma_f32_16x16x32_bf16 v[30:33], v[156:159], v[196:199], v[30:33]
	v_mfma_f32_16x16x32_bf16 v[22:25], v[148:151], v[212:215], v[22:25]
	v_mfma_f32_16x16x32_bf16 v[14:17], v[156:159], v[212:215], v[14:17]
	s_setprio 0
	s_setprio 1
	v_mfma_f32_16x16x32_bf16 v[50:53], v[160:163], v[176:179], v[50:53]
	v_mfma_f32_16x16x32_bf16 v[42:45], v[168:171], v[176:179], v[42:45]
	v_mfma_f32_16x16x32_bf16 v[34:37], v[160:163], v[184:187], v[34:37]
	v_mfma_f32_16x16x32_bf16 v[26:29], v[168:171], v[184:187], v[26:29]
	v_mfma_f32_16x16x32_bf16 v[18:21], v[160:163], v[192:195], v[18:21]
	v_mfma_f32_16x16x32_bf16 v[10:13], v[168:171], v[192:195], v[10:13]
	v_mfma_f32_16x16x32_bf16 v[6:9], v[160:163], v[200:203], v[6:9]
	v_mfma_f32_16x16x32_bf16 v[2:5], v[168:171], v[200:203], v[2:5]
	v_mfma_f32_16x16x32_bf16 v[50:53], v[164:167], v[180:183], v[50:53]
	v_mfma_f32_16x16x32_bf16 v[42:45], v[172:175], v[180:183], v[42:45]
	v_mfma_f32_16x16x32_bf16 v[34:37], v[164:167], v[188:191], v[34:37]
	v_mfma_f32_16x16x32_bf16 v[26:29], v[172:175], v[188:191], v[26:29]
	v_mfma_f32_16x16x32_bf16 v[18:21], v[164:167], v[196:199], v[18:21]
	v_mfma_f32_16x16x32_bf16 v[10:13], v[172:175], v[196:199], v[10:13]
	v_mfma_f32_16x16x32_bf16 v[6:9], v[164:167], v[212:215], v[6:9]
	v_mfma_f32_16x16x32_bf16 v[2:5], v[172:175], v[212:215], v[2:5]
	s_setprio 0
	s_barrier
	s_add_i32 s70, s70, 2
	s_add_u32 s46, s46, 0x100
	s_addc_u32 s47, s47, 0
	s_add_u32 s68, s68, 0x100
	s_addc_u32 s69, s69, 0
	s_cmp_gt_u32 s70, 13
	s_cbranch_scc0 .LBB0_197
	s_and_b64 vcc, exec, s[26:27]
	s_cbranch_vccz .LBB0_200
	s_barrier

; #define PG8_STAGE(bufoff, gbase, voff) do { _Pragma("unroll") for (int _i = 0; _i < 2; ++_i) \
;         __builtin_amdgcn_global_load_lds((const unsigned*)((const char*)(gbase) + (voff)[_i]), (PG8_LAS unsigned*)(lds + (bufoff) + ldsw + _i * 8192), 16, 0, 0); } while (0)
; #define PG8_LDA(dst, b, h) do { _Pragma("unroll") for (int m = 0; m < 4; ++m) _Pragma("unroll") for (int k = 0; k < 2; ++k) dst[m][k] = *(const PG8_LAS bf16x8*)(lds + PG8_SA(b, h) + aoff + m * 2048 + k * 1024); } while (0)
; #define PG8_LDB(dst, b, h) do { _Pragma("unroll") for (int n = 0; n < 2; ++n) _Pragma("unroll") for (int k = 0; k < 2; ++k) dst[n][k] = *(const PG8_LAS bf16x8*)(lds + PG8_SB(b, h) + boff + n * 2048 + k * 1024); } while (0)
; #define PG8_WAIT_V(n) asm volatile("s_waitcnt vmcnt(" #n ")" ::: "memory")
; #define PG8_WAIT_L(n) asm volatile("s_waitcnt lgkmcnt(" #n ")" ::: "memory")
; template <class Epi, class Sched, bool ALIGN_EPI = false, bool SP2 = false>
; __device__ __forceinline__ void gemm_phase(PG8_LAS unsigned char* lds, const Gemm g, const Sched& S, const Epi& E) {
;     ...
;     for (;;) {
;         const bool has_next = S.next(ui + 1, nxt);
;         const char* nA = has_next ? (const char*)g.A + (size_t)nxt.pm * tstep + (size_t)nxt.k0 * 2 : cA; const char* nB = has_next ? (const char*)g.Bt + (size_t)nxt.pn * tstep + (size_t)nxt.k0 * 2 : cB;
;         const int unt = cur.nt ? cur.nt : nt;
;         for (int t = 0; t < unt; t += 2) {
;             const bool last = (t == unt - 2);
;             const char* a1 = cA + (size_t)(t + 1) * kstep;
;             const char* a2 = last ? nA : cA + (size_t)(t + 2) * kstep; const char* b2 = last ? nB : cB + (size_t)(t + 2) * kstep;
;             const char* a3 = a2 + kstep; const char* b3 = b2 + kstep;
;             if (last && has_next) S.a_ready(nxt);
;             if constexpr (SP2) {
;             PG8_LDB(B0, 0, 0); PG8_LDB(B1, 0, 1); PG8_SCHED; PG8_LDA(At, 0, 0); PG8_STAGE(PG8_SA(1, 1), a1 + hstep, voffA);
;             PG8_WAIT_V(8); PG8_WAIT_L(0); PG8_BAR; PG8_MMA(0, 0, At, B0); PG8_MMA(0, 1, At, B1); PG8_BAR; PG8_SCHED;
;             PG8_LDA(At, 0, 1); PG8_STAGE(PG8_SB(0, 0), b2, voffB); PG8_STAGE(PG8_SB(0, 1), b2 + hstep, voffB); PG8_STAGE(PG8_SA(0, 0), a2, voffA);
;             PG8_WAIT_V(8); PG8_WAIT_L(0); PG8_BAR; PG8_MMA(1, 0, At, B0); PG8_MMA(1, 1, At, B1); PG8_BAR; PG8_SCHED;
.LBB0_768:
	s_add_i32 s53, s51, 2
	s_add_u32 s40, s34, 0x100
	s_addc_u32 s41, s35, 0
	s_add_i32 s6, 0, 0x10000
	s_cmp_eq_u32 s5, s51
	s_cselect_b32 s63, s57, s41
	s_cselect_b32 s62, s56, s40
	s_cselect_b32 s61, s59, s27
	s_cselect_b32 s60, s58, s25
	s_add_i32 s51, 0, 0x14000
	s_waitcnt vmcnt(0)
	v_add_u32_e32 v78, s6, v163
	v_add_u32_e32 v160, s51, v163
	ds_read_b128 v[54:57], v78
	ds_read_b128 v[62:65], v78 offset:1024
	ds_read_b128 v[70:73], v78 offset:2048
	ds_read_b128 v[78:81], v78 offset:3072
	ds_read_b128 v[152:155], v160
	ds_read_b128 v[156:159], v160 offset:1024
	ds_read_b128 v[166:169], v160 offset:2048
	ds_read_b128 v[170:173], v160 offset:3072
	s_add_i32 m0, s45, 0xc000
	ds_read_b128 v[174:177], v165
	ds_read_b128 v[178:181], v165 offset:1024
	ds_read_b128 v[182:185], v165 offset:2048
	ds_read_b128 v[186:189], v165 offset:3072
	ds_read_b128 v[190:193], v165 offset:4096
	ds_read_b128 v[194:197], v165 offset:5120
	ds_read_b128 v[198:201], v165 offset:6144
	ds_read_b128 v[202:205], v165 offset:7168
	global_load_lds_dwordx4 v148, s[34:35]
	s_add_i32 m0, s45, 0xe000
	s_nop 0
	global_load_lds_dwordx4 v150, s[34:35]
	s_waitcnt vmcnt(8)
	s_waitcnt lgkmcnt(0)
	s_barrier
	s_setprio 1
	v_mfma_f32_16x16x32_bf16 v[142:145], v[54:57], v[174:177], v[142:145]
	v_mfma_f32_16x16x32_bf16 v[138:141], v[70:73], v[174:177], v[138:141]
	v_mfma_f32_16x16x32_bf16 v[126:129], v[54:57], v[182:185], v[126:129]
	v_mfma_f32_16x16x32_bf16 v[122:125], v[70:73], v[182:185], v[122:125]
	v_mfma_f32_16x16x32_bf16 v[110:113], v[54:57], v[190:193], v[110:113]
	v_mfma_f32_16x16x32_bf16 v[106:109], v[70:73], v[190:193], v[106:109]
	v_mfma_f32_16x16x32_bf16 v[94:97], v[54:57], v[198:201], v[94:97]
	v_mfma_f32_16x16x32_bf16 v[90:93], v[70:73], v[198:201], v[90:93]
	v_mfma_f32_16x16x32_bf16 v[142:145], v[62:65], v[178:181], v[142:145]
	v_mfma_f32_16x16x32_bf16 v[138:141], v[78:81], v[178:181], v[138:141]
	v_mfma_f32_16x16x32_bf16 v[126:129], v[62:65], v[186:189], v[126:129]
	v_mfma_f32_16x16x32_bf16 v[122:125], v[78:81], v[186:189], v[122:125]
	v_mfma_f32_16x16x32_bf16 v[110:113], v[62:65], v[194:197], v[110:113]
	v_mfma_f32_16x16x32_bf16 v[106:109], v[78:81], v[194:197], v[106:109]
	v_mfma_f32_16x16x32_bf16 v[94:97], v[62:65], v[202:205], v[94:97]
	v_mfma_f32_16x16x32_bf16 v[90:93], v[78:81], v[202:205], v[90:93]
	s_setprio 0
	s_setprio 1
	v_mfma_f32_16x16x32_bf16 v[134:137], v[152:155], v[174:177], v[134:137]
	v_mfma_f32_16x16x32_bf16 v[130:133], v[166:169], v[174:177], v[130:133]
	v_mfma_f32_16x16x32_bf16 v[118:121], v[152:155], v[182:185], v[118:121]
	v_mfma_f32_16x16x32_bf16 v[114:117], v[166:169], v[182:185], v[114:117]
	v_mfma_f32_16x16x32_bf16 v[102:105], v[152:155], v[190:193], v[102:105]
	v_mfma_f32_16x16x32_bf16 v[98:101], v[166:169], v[190:193], v[98:101]
	v_mfma_f32_16x16x32_bf16 v[86:89], v[152:155], v[198:201], v[86:89]
	v_mfma_f32_16x16x32_bf16 v[82:85], v[166:169], v[198:201], v[82:85]
	v_mfma_f32_16x16x32_bf16 v[134:137], v[156:159], v[178:181], v[134:137]
	v_mfma_f32_16x16x32_bf16 v[130:133], v[170:173], v[178:181], v[130:133]
	v_mfma_f32_16x16x32_bf16 v[118:121], v[156:159], v[186:189], v[118:121]
	v_mfma_f32_16x16x32_bf16 v[114:117], v[170:173], v[186:189], v[114:117]
	v_mfma_f32_16x16x32_bf16 v[102:105], v[156:159], v[194:197], v[102:105]
	v_mfma_f32_16x16x32_bf16 v[98:101], v[170:173], v[194:197], v[98:101]
	v_mfma_f32_16x16x32_bf16 v[86:89], v[156:159], v[202:205], v[86:89]
	v_mfma_f32_16x16x32_bf16 v[82:85], v[170:173], v[202:205], v[82:85]
	s_setprio 0
	s_barrier
	s_add_i32 s6, s6, s69
	s_add_u32 s98, s60, s22
	s_addc_u32 s99, s61, s23
	s_mov_b32 m0, s6
	ds_read_b128 v[174:177], v165 offset:16384
	ds_read_b128 v[178:181], v165 offset:17408
	ds_read_b128 v[182:185], v165 offset:18432
	ds_read_b128 v[186:189], v165 offset:19456
	ds_read_b128 v[190:193], v165 offset:20480
	ds_read_b128 v[194:197], v165 offset:21504
	ds_read_b128 v[198:201], v165 offset:22528
	ds_read_b128 v[202:205], v165 offset:23552
	global_load_lds_dwordx4 v0, s[60:61]
	s_add_i32 m0, s6, 0x2000
	s_add_u32 s6, s60, 0x40000
	s_addc_u32 s7, s61, 0
	s_add_i32 s34, s51, s69
	global_load_lds_dwordx4 v146, s[60:61]
	s_mov_b32 m0, s34
	s_add_u32 s100, s62, s22
	s_addc_u32 s101, s63, s23
	global_load_lds_dwordx4 v0, s[6:7]
	s_add_i32 m0, s34, 0x2000
	s_nop 0
	global_load_lds_dwordx4 v146, s[6:7]
	s_mov_b32 m0, s45
	s_nop 0
	global_load_lds_dwordx4 v0, s[62:63]
	s_mov_b32 m0, s82
	s_nop 0
	global_load_lds_dwordx4 v146, s[62:63]
	s_waitcnt vmcnt(8)
	s_waitcnt lgkmcnt(0)
	s_barrier
	s_setprio 1
	v_mfma_f32_16x16x32_bf16 v[74:77], v[54:57], v[174:177], v[74:77]
	v_mfma_f32_16x16x32_bf16 v[66:69], v[70:73], v[174:177], v[66:69]
	v_mfma_f32_16x16x32_bf16 v[46:49], v[54:57], v[182:185], v[46:49]
	v_mfma_f32_16x16x32_bf16 v[42:45], v[70:73], v[182:185], v[42:45]
	v_mfma_f32_16x16x32_bf16 v[30:33], v[54:57], v[190:193], v[30:33]
	v_mfma_f32_16x16x32_bf16 v[26:29], v[70:73], v[190:193], v[26:29]
	v_mfma_f32_16x16x32_bf16 v[14:17], v[54:57], v[198:201], v[14:17]
	v_mfma_f32_16x16x32_bf16 v[10:13], v[70:73], v[198:201], v[10:13]
	v_mfma_f32_16x16x32_bf16 v[74:77], v[62:65], v[178:181], v[74:77]
	v_mfma_f32_16x16x32_bf16 v[66:69], v[78:81], v[178:181], v[66:69]
	v_mfma_f32_16x16x32_bf16 v[46:49], v[62:65], v[186:189], v[46:49]
	v_mfma_f32_16x16x32_bf16 v[42:45], v[78:81], v[186:189], v[42:45]
	v_mfma_f32_16x16x32_bf16 v[30:33], v[62:65], v[194:197], v[30:33]
	v_mfma_f32_16x16x32_bf16 v[26:29], v[78:81], v[194:197], v[26:29]
	v_mfma_f32_16x16x32_bf16 v[14:17], v[62:65], v[202:205], v[14:17]
	v_mfma_f32_16x16x32_bf16 v[10:13], v[78:81], v[202:205], v[10:13]
	s_setprio 0
	s_setprio 1
	v_mfma_f32_16x16x32_bf16 v[50:53], v[166:169], v[174:177], v[50:53]
	v_mfma_f32_16x16x32_bf16 v[38:41], v[152:155], v[182:185], v[38:41]
	v_mfma_f32_16x16x32_bf16 v[34:37], v[166:169], v[182:185], v[34:37]
	v_mfma_f32_16x16x32_bf16 v[22:25], v[152:155], v[190:193], v[22:25]
	v_mfma_f32_16x16x32_bf16 v[18:21], v[166:169], v[190:193], v[18:21]
	v_mfma_f32_16x16x32_bf16 v[6:9], v[152:155], v[198:201], v[6:9]
	v_mfma_f32_16x16x32_bf16 v[2:5], v[166:169], v[198:201], v[2:5]
	v_mfma_f32_16x16x32_bf16 v[54:57], v[152:155], v[174:177], v[58:61]
	v_mfma_f32_16x16x32_bf16 v[50:53], v[170:173], v[178:181], v[50:53]
	v_mfma_f32_16x16x32_bf16 v[38:41], v[156:159], v[186:189], v[38:41]
	v_mfma_f32_16x16x32_bf16 v[34:37], v[170:173], v[186:189], v[34:37]
	v_mfma_f32_16x16x32_bf16 v[22:25], v[156:159], v[194:197], v[22:25]
	v_mfma_f32_16x16x32_bf16 v[18:21], v[170:173], v[194:197], v[18:21]
	v_mfma_f32_16x16x32_bf16 v[6:9], v[156:159], v[202:205], v[6:9]
	v_mfma_f32_16x16x32_bf16 v[2:5], v[170:173], v[202:205], v[2:5]
	v_mfma_f32_16x16x32_bf16 v[54:57], v[156:159], v[178:181], v[54:57]
	s_setprio 0
	s_barrier
; #define PG8_STAGE(bufoff, gbase, voff) do { _Pragma("unroll") for (int _i = 0; _i < 2; ++_i) \
;         __builtin_amdgcn_global_load_lds((const unsigned*)((const char*)(gbase) + (voff)[_i]), (PG8_LAS unsigned*)(lds + (bufoff) + ldsw + _i * 8192), 16, 0, 0); } while (0)
; #define PG8_LDA(dst, b, h) do { _Pragma("unroll") for (int m = 0; m < 4; ++m) _Pragma("unroll") for (int k = 0; k < 2; ++k) dst[m][k] = *(const PG8_LAS bf16x8*)(lds + PG8_SA(b, h) + aoff + m * 2048 + k * 1024); } while (0)
; #define PG8_LDB(dst, b, h) do { _Pragma("unroll") for (int n = 0; n < 2; ++n) _Pragma("unroll") for (int k = 0; k < 2; ++k) dst[n][k] = *(const PG8_LAS bf16x8*)(lds + PG8_SB(b, h) + boff + n * 2048 + k * 1024); } while (0)
; template <class Epi, class Sched, bool ALIGN_EPI = false, bool SP2 = false>
; __device__ __forceinline__ void gemm_phase(PG8_LAS unsigned char* lds, const Gemm g, const Sched& S, const Epi& E) {
;     ...
;         for (int t = 0; t < unt; t += 2) {
;             const bool last = (t == unt - 2);
;             const char* a1 = cA + (size_t)(t + 1) * kstep;
;             const char* a2 = last ? nA : cA + (size_t)(t + 2) * kstep; const char* b2 = last ? nB : cB + (size_t)(t + 2) * kstep;
;             const char* a3 = a2 + kstep; const char* b3 = b2 + kstep;
;             if (last && has_next) S.a_ready(nxt);
;             if constexpr (SP2) {
;             PG8_LDB(B0, 0, 0); PG8_LDB(B1, 0, 1); PG8_SCHED; PG8_LDA(At, 0, 0); PG8_STAGE(PG8_SA(1, 1), a1 + hstep, voffA);
;             PG8_WAIT_V(8); PG8_WAIT_L(0); PG8_BAR; PG8_MMA(0, 0, At, B0); PG8_MMA(0, 1, At, B1); PG8_BAR; PG8_SCHED;
;             PG8_LDA(At, 0, 1); PG8_STAGE(PG8_SB(0, 0), b2, voffB); PG8_STAGE(PG8_SB(0, 1), b2 + hstep, voffB); PG8_STAGE(PG8_SA(0, 0), a2, voffA);
;             PG8_WAIT_V(8); PG8_WAIT_L(0); PG8_BAR; PG8_MMA(1, 0, At, B0); PG8_MMA(1, 1, At, B1); PG8_BAR; PG8_SCHED;
;             PG8_LDB(B0, 1, 0); PG8_LDB(B1, 1, 1); PG8_SCHED; PG8_LDA(At, 1, 0); PG8_STAGE(PG8_SA(0, 1), a2 + hstep, voffA);
;             PG8_WAIT_V(8); PG8_WAIT_L(0); PG8_BAR; PG8_MMA(0, 0, At, B0); PG8_MMA(0, 1, At, B1); PG8_BAR; PG8_SCHED;
;             PG8_LDA(At, 1, 1); PG8_STAGE(PG8_SB(1, 0), b3, voffB); PG8_STAGE(PG8_SB(1, 1), b3 + hstep, voffB); PG8_STAGE(PG8_SA(1, 0), a3, voffA);
;             PG8_WAIT_V(8); PG8_WAIT_L(0); PG8_BAR; PG8_MMA(1, 0, At, B0); PG8_MMA(1, 1, At, B1); PG8_BAR; PG8_SCHED;
	s_add_i32 s34, 0, 0x18000
	s_add_i32 s35, 0, 0x1c000
	v_add_u32_e32 v78, s34, v163
	v_add_u32_e32 v170, s35, v163
	ds_read_b128 v[58:61], v78
	ds_read_b128 v[62:65], v78 offset:1024
	ds_read_b128 v[70:73], v78 offset:2048
	ds_read_b128 v[78:81], v78 offset:3072
	ds_read_b128 v[152:155], v170
	ds_read_b128 v[156:159], v170 offset:1024
	ds_read_b128 v[166:169], v170 offset:2048
	ds_read_b128 v[170:173], v170 offset:3072
	s_add_u32 s6, s62, 0x40000
	s_addc_u32 s7, s63, 0
	s_mov_b32 m0, s83
	ds_read_b128 v[174:177], v165 offset:32768
	ds_read_b128 v[178:181], v165 offset:33792
	ds_read_b128 v[182:185], v165 offset:34816
	ds_read_b128 v[186:189], v165 offset:35840
	ds_read_b128 v[190:193], v165 offset:36864
	ds_read_b128 v[194:197], v165 offset:37888
	ds_read_b128 v[198:201], v165 offset:38912
	ds_read_b128 v[202:205], v165 offset:39936
	global_load_lds_dwordx4 v0, s[6:7]
	s_mov_b32 m0, s84
	s_nop 0
	global_load_lds_dwordx4 v146, s[6:7]
	s_waitcnt vmcnt(8)
	s_waitcnt lgkmcnt(0)
	s_barrier
	s_setprio 1
	v_mfma_f32_16x16x32_bf16 v[142:145], v[58:61], v[174:177], v[142:145]
	v_mfma_f32_16x16x32_bf16 v[138:141], v[70:73], v[174:177], v[138:141]
	v_mfma_f32_16x16x32_bf16 v[126:129], v[58:61], v[182:185], v[126:129]
	v_mfma_f32_16x16x32_bf16 v[122:125], v[70:73], v[182:185], v[122:125]
	v_mfma_f32_16x16x32_bf16 v[110:113], v[58:61], v[190:193], v[110:113]
	v_mfma_f32_16x16x32_bf16 v[106:109], v[70:73], v[190:193], v[106:109]
	v_mfma_f32_16x16x32_bf16 v[94:97], v[58:61], v[198:201], v[94:97]
	v_mfma_f32_16x16x32_bf16 v[90:93], v[70:73], v[198:201], v[90:93]
	v_mfma_f32_16x16x32_bf16 v[142:145], v[62:65], v[178:181], v[142:145]
	v_mfma_f32_16x16x32_bf16 v[138:141], v[78:81], v[178:181], v[138:141]
	v_mfma_f32_16x16x32_bf16 v[126:129], v[62:65], v[186:189], v[126:129]
	v_mfma_f32_16x16x32_bf16 v[122:125], v[78:81], v[186:189], v[122:125]
	v_mfma_f32_16x16x32_bf16 v[110:113], v[62:65], v[194:197], v[110:113]
	v_mfma_f32_16x16x32_bf16 v[106:109], v[78:81], v[194:197], v[106:109]
	v_mfma_f32_16x16x32_bf16 v[94:97], v[62:65], v[202:205], v[94:97]
	v_mfma_f32_16x16x32_bf16 v[90:93], v[78:81], v[202:205], v[90:93]
	s_setprio 0
	s_setprio 1
	v_mfma_f32_16x16x32_bf16 v[134:137], v[152:155], v[174:177], v[134:137]
	v_mfma_f32_16x16x32_bf16 v[130:133], v[166:169], v[174:177], v[130:133]
	v_mfma_f32_16x16x32_bf16 v[118:121], v[152:155], v[182:185], v[118:121]
	v_mfma_f32_16x16x32_bf16 v[114:117], v[166:169], v[182:185], v[114:117]
	v_mfma_f32_16x16x32_bf16 v[102:105], v[152:155], v[190:193], v[102:105]
	v_mfma_f32_16x16x32_bf16 v[98:101], v[166:169], v[190:193], v[98:101]
	v_mfma_f32_16x16x32_bf16 v[86:89], v[152:155], v[198:201], v[86:89]
	v_mfma_f32_16x16x32_bf16 v[82:85], v[166:169], v[198:201], v[82:85]
	v_mfma_f32_16x16x32_bf16 v[134:137], v[156:159], v[178:181], v[134:137]
	v_mfma_f32_16x16x32_bf16 v[130:133], v[170:173], v[178:181], v[130:133]
	v_mfma_f32_16x16x32_bf16 v[118:121], v[156:159], v[186:189], v[118:121]
	v_mfma_f32_16x16x32_bf16 v[114:117], v[170:173], v[186:189], v[114:117]
	v_mfma_f32_16x16x32_bf16 v[102:105], v[156:159], v[194:197], v[102:105]
	v_mfma_f32_16x16x32_bf16 v[98:101], v[170:173], v[194:197], v[98:101]
	v_mfma_f32_16x16x32_bf16 v[86:89], v[156:159], v[202:205], v[86:89]
	v_mfma_f32_16x16x32_bf16 v[82:85], v[170:173], v[202:205], v[82:85]
	s_setprio 0
	s_barrier
	s_add_i32 s6, s34, s69
	s_mov_b32 m0, s6
	ds_read_b128 v[174:177], v165 offset:49152
	ds_read_b128 v[178:181], v165 offset:50176
	ds_read_b128 v[182:185], v165 offset:51200
	ds_read_b128 v[186:189], v165 offset:52224
	ds_read_b128 v[190:193], v165 offset:53248
	ds_read_b128 v[194:197], v165 offset:54272
	ds_read_b128 v[198:201], v165 offset:55296
	ds_read_b128 v[202:205], v165 offset:56320
	global_load_lds_dwordx4 v0, s[98:99]
	s_add_i32 m0, s6, 0x2000
	s_add_u32 s6, s60, 0x40080
	s_addc_u32 s7, s61, 0
	s_add_i32 s34, s35, s69
	global_load_lds_dwordx4 v146, s[98:99]
	s_mov_b32 m0, s34
	s_nop 0
	global_load_lds_dwordx4 v0, s[6:7]
	s_add_i32 m0, s34, 0x2000
	s_nop 0
	global_load_lds_dwordx4 v146, s[6:7]
	s_mov_b32 m0, s93
	s_nop 0
	global_load_lds_dwordx4 v0, s[100:101]
	s_mov_b32 m0, s94
	s_nop 0
	global_load_lds_dwordx4 v146, s[100:101]
	s_waitcnt vmcnt(8)
	s_waitcnt lgkmcnt(0)
	s_barrier
	s_setprio 1
	v_mfma_f32_16x16x32_bf16 v[74:77], v[58:61], v[174:177], v[74:77]
	v_mfma_f32_16x16x32_bf16 v[66:69], v[70:73], v[174:177], v[66:69]
	v_mfma_f32_16x16x32_bf16 v[46:49], v[58:61], v[182:185], v[46:49]
	v_mfma_f32_16x16x32_bf16 v[42:45], v[70:73], v[182:185], v[42:45]
	v_mfma_f32_16x16x32_bf16 v[30:33], v[58:61], v[190:193], v[30:33]
	v_mfma_f32_16x16x32_bf16 v[26:29], v[70:73], v[190:193], v[26:29]
	v_mfma_f32_16x16x32_bf16 v[14:17], v[58:61], v[198:201], v[14:17]
	v_mfma_f32_16x16x32_bf16 v[10:13], v[70:73], v[198:201], v[10:13]
	v_mfma_f32_16x16x32_bf16 v[74:77], v[62:65], v[178:181], v[74:77]
	v_mfma_f32_16x16x32_bf16 v[66:69], v[78:81], v[178:181], v[66:69]
	v_mfma_f32_16x16x32_bf16 v[46:49], v[62:65], v[186:189], v[46:49]
	v_mfma_f32_16x16x32_bf16 v[42:45], v[78:81], v[186:189], v[42:45]
	v_mfma_f32_16x16x32_bf16 v[30:33], v[62:65], v[194:197], v[30:33]
	v_mfma_f32_16x16x32_bf16 v[26:29], v[78:81], v[194:197], v[26:29]
	v_mfma_f32_16x16x32_bf16 v[14:17], v[62:65], v[202:205], v[14:17]
	v_mfma_f32_16x16x32_bf16 v[10:13], v[78:81], v[202:205], v[10:13]
	s_setprio 0
	s_setprio 1
	v_mfma_f32_16x16x32_bf16 v[54:57], v[152:155], v[174:177], v[54:57]
	v_mfma_f32_16x16x32_bf16 v[50:53], v[166:169], v[174:177], v[50:53]
	v_mfma_f32_16x16x32_bf16 v[38:41], v[152:155], v[182:185], v[38:41]
	v_mfma_f32_16x16x32_bf16 v[34:37], v[166:169], v[182:185], v[34:37]
	v_mfma_f32_16x16x32_bf16 v[22:25], v[152:155], v[190:193], v[22:25]
	v_mfma_f32_16x16x32_bf16 v[18:21], v[166:169], v[190:193], v[18:21]
	v_mfma_f32_16x16x32_bf16 v[6:9], v[152:155], v[198:201], v[6:9]
	v_mfma_f32_16x16x32_bf16 v[2:5], v[166:169], v[198:201], v[2:5]
	v_mfma_f32_16x16x32_bf16 v[58:61], v[156:159], v[178:181], v[54:57]
	v_mfma_f32_16x16x32_bf16 v[50:53], v[170:173], v[178:181], v[50:53]
	v_mfma_f32_16x16x32_bf16 v[38:41], v[156:159], v[186:189], v[38:41]
	v_mfma_f32_16x16x32_bf16 v[34:37], v[170:173], v[186:189], v[34:37]
	v_mfma_f32_16x16x32_bf16 v[22:25], v[156:159], v[194:197], v[22:25]
	v_mfma_f32_16x16x32_bf16 v[18:21], v[170:173], v[194:197], v[18:21]
	v_mfma_f32_16x16x32_bf16 v[6:9], v[156:159], v[202:205], v[6:9]
	v_mfma_f32_16x16x32_bf16 v[2:5], v[170:173], v[202:205], v[2:5]
	s_setprio 0
	s_barrier
	s_add_u32 s25, s25, 0x100
	s_addc_u32 s27, s27, 0
	s_cmp_ge_i32 s53, s4
	s_mov_b64 s[34:35], s[40:41]
	s_mov_b32 s51, s53
	s_cbranch_scc0 .LBB0_768
	s_and_b64 vcc, exec, s[48:49]
	s_cbranch_vccz .LBB0_771

; #define PG8_STAGE(bufoff, gbase, voff) do { _Pragma("unroll") for (int _i = 0; _i < 2; ++_i) \
;         __builtin_amdgcn_global_load_lds((const unsigned*)((const char*)(gbase) + (voff)[_i]), (PG8_LAS unsigned*)(lds + (bufoff) + ldsw + _i * 8192), 16, 0, 0); } while (0)
; #define PG8_LDA(dst, b, h) do { _Pragma("unroll") for (int m = 0; m < 4; ++m) _Pragma("unroll") for (int k = 0; k < 2; ++k) dst[m][k] = *(const PG8_LAS bf16x8*)(lds + PG8_SA(b, h) + aoff + m * 2048 + k * 1024); } while (0)
; #define PG8_LDB(dst, b, h) do { _Pragma("unroll") for (int n = 0; n < 2; ++n) _Pragma("unroll") for (int k = 0; k < 2; ++k) dst[n][k] = *(const PG8_LAS bf16x8*)(lds + PG8_SB(b, h) + boff + n * 2048 + k * 1024); } while (0)
; #define PG8_WAIT_V(n) asm volatile("s_waitcnt vmcnt(" #n ")" ::: "memory")
; #define PG8_WAIT_L(n) asm volatile("s_waitcnt lgkmcnt(" #n ")" ::: "memory")
; template <class Epi, class Sched, bool ALIGN_EPI = false, bool SP2 = false>
; __device__ __forceinline__ void gemm_phase(PG8_LAS unsigned char* lds, const Gemm g, const Sched& S, const Epi& E) {
;     ...
;     for (;;) {
;         const bool has_next = S.next(ui + 1, nxt);
;         const char* nA = has_next ? (const char*)g.A + (size_t)nxt.pm * tstep + (size_t)nxt.k0 * 2 : cA; const char* nB = has_next ? (const char*)g.Bt + (size_t)nxt.pn * tstep + (size_t)nxt.k0 * 2 : cB;
;         const int unt = cur.nt ? cur.nt : nt;
;         for (int t = 0; t < unt; t += 2) {
;             const bool last = (t == unt - 2);
;             const char* a1 = cA + (size_t)(t + 1) * kstep;
;             const char* a2 = last ? nA : cA + (size_t)(t + 2) * kstep; const char* b2 = last ? nB : cB + (size_t)(t + 2) * kstep;
;             const char* a3 = a2 + kstep; const char* b3 = b2 + kstep;
;             if (last && has_next) S.a_ready(nxt);
;             if constexpr (SP2) {
;             PG8_LDB(B0, 0, 0); PG8_LDB(B1, 0, 1); PG8_SCHED; PG8_LDA(At, 0, 0); PG8_STAGE(PG8_SA(1, 1), a1 + hstep, voffA);
;             PG8_WAIT_V(8); PG8_WAIT_L(0); PG8_BAR; PG8_MMA(0, 0, At, B0); PG8_MMA(0, 1, At, B1); PG8_BAR; PG8_SCHED;
;             PG8_LDA(At, 0, 1); PG8_STAGE(PG8_SB(0, 0), b2, voffB); PG8_STAGE(PG8_SB(0, 1), b2 + hstep, voffB); PG8_STAGE(PG8_SA(0, 0), a2, voffA);
;             PG8_WAIT_V(8); PG8_WAIT_L(0); PG8_BAR; PG8_MMA(1, 0, At, B0); PG8_MMA(1, 1, At, B1); PG8_BAR; PG8_SCHED;
.LBB0_1026:
	s_add_u32 s6, s46, 0xfffc0080
	s_addc_u32 s7, s47, -1
	s_add_i32 s76, 0, 0x10000
	s_cmp_eq_u32 s71, 12
	s_cselect_b32 s51, s5, s7
	s_cselect_b32 s50, s35, s6
	v_add_u32_e32 v140, s76, v143
	s_cselect_b32 s49, s31, s70
	s_cselect_b32 s48, s68, s69
	s_add_i32 s77, 0, 0x14000
	ds_read_b128 v[146:149], v140
	ds_read_b128 v[150:153], v140 offset:1024
	ds_read_b128 v[154:157], v140 offset:2048
	ds_read_b128 v[158:161], v140 offset:3072
	v_add_u32_e32 v140, s77, v143
	ds_read_b128 v[162:165], v140
	ds_read_b128 v[166:169], v140 offset:1024
	ds_read_b128 v[170:173], v140 offset:2048
	ds_read_b128 v[174:177], v140 offset:3072
	s_add_i32 m0, s45, 0xc000
	ds_read_b128 v[178:181], v145
	ds_read_b128 v[182:185], v145 offset:1024
	ds_read_b128 v[186:189], v145 offset:2048
	ds_read_b128 v[190:193], v145 offset:3072
	ds_read_b128 v[194:197], v145 offset:4096
	ds_read_b128 v[198:201], v145 offset:5120
	ds_read_b128 v[202:205], v145 offset:6144
	ds_read_b128 v[212:215], v145 offset:7168
	global_load_lds_dwordx4 v136, s[46:47]
	s_add_i32 m0, s45, 0xe000
	s_nop 0
	global_load_lds_dwordx4 v138, s[46:47]
	s_waitcnt vmcnt(8)
	s_waitcnt lgkmcnt(0)
	s_barrier
	s_setprio 1
	v_mfma_f32_16x16x32_bf16 v[126:129], v[146:149], v[178:181], v[126:129]
	v_mfma_f32_16x16x32_bf16 v[122:125], v[154:157], v[178:181], v[122:125]
	v_mfma_f32_16x16x32_bf16 v[110:113], v[146:149], v[186:189], v[110:113]
	v_mfma_f32_16x16x32_bf16 v[106:109], v[154:157], v[186:189], v[106:109]
	v_mfma_f32_16x16x32_bf16 v[94:97], v[146:149], v[194:197], v[94:97]
	v_mfma_f32_16x16x32_bf16 v[90:93], v[154:157], v[194:197], v[90:93]
	v_mfma_f32_16x16x32_bf16 v[78:81], v[146:149], v[202:205], v[78:81]
	v_mfma_f32_16x16x32_bf16 v[74:77], v[154:157], v[202:205], v[74:77]
	v_mfma_f32_16x16x32_bf16 v[126:129], v[150:153], v[182:185], v[126:129]
	v_mfma_f32_16x16x32_bf16 v[122:125], v[158:161], v[182:185], v[122:125]
	v_mfma_f32_16x16x32_bf16 v[110:113], v[150:153], v[190:193], v[110:113]
	v_mfma_f32_16x16x32_bf16 v[106:109], v[158:161], v[190:193], v[106:109]
	v_mfma_f32_16x16x32_bf16 v[94:97], v[150:153], v[198:201], v[94:97]
	v_mfma_f32_16x16x32_bf16 v[90:93], v[158:161], v[198:201], v[90:93]
	v_mfma_f32_16x16x32_bf16 v[78:81], v[150:153], v[212:215], v[78:81]
	v_mfma_f32_16x16x32_bf16 v[74:77], v[158:161], v[212:215], v[74:77]
	s_setprio 0
	s_setprio 1
	v_mfma_f32_16x16x32_bf16 v[118:121], v[162:165], v[178:181], v[118:121]
	v_mfma_f32_16x16x32_bf16 v[114:117], v[170:173], v[178:181], v[114:117]
	v_mfma_f32_16x16x32_bf16 v[102:105], v[162:165], v[186:189], v[102:105]
	v_mfma_f32_16x16x32_bf16 v[98:101], v[170:173], v[186:189], v[98:101]
	v_mfma_f32_16x16x32_bf16 v[86:89], v[162:165], v[194:197], v[86:89]
	v_mfma_f32_16x16x32_bf16 v[82:85], v[170:173], v[194:197], v[82:85]
	v_mfma_f32_16x16x32_bf16 v[70:73], v[162:165], v[202:205], v[70:73]
	v_mfma_f32_16x16x32_bf16 v[66:69], v[170:173], v[202:205], v[66:69]
	v_mfma_f32_16x16x32_bf16 v[118:121], v[166:169], v[182:185], v[118:121]
	v_mfma_f32_16x16x32_bf16 v[114:117], v[174:177], v[182:185], v[114:117]
	v_mfma_f32_16x16x32_bf16 v[102:105], v[166:169], v[190:193], v[102:105]
	v_mfma_f32_16x16x32_bf16 v[98:101], v[174:177], v[190:193], v[98:101]
	v_mfma_f32_16x16x32_bf16 v[86:89], v[166:169], v[198:201], v[86:89]
	v_mfma_f32_16x16x32_bf16 v[82:85], v[174:177], v[198:201], v[82:85]
	v_mfma_f32_16x16x32_bf16 v[70:73], v[166:169], v[212:215], v[70:73]
	v_mfma_f32_16x16x32_bf16 v[66:69], v[174:177], v[212:215], v[66:69]
	s_setprio 0
	s_barrier
	s_add_i32 s6, s76, s60
	s_add_u32 s98, s48, s22
	s_addc_u32 s99, s49, s23
	s_mov_b32 m0, s6
	ds_read_b128 v[178:181], v145 offset:16384
	ds_read_b128 v[182:185], v145 offset:17408
	ds_read_b128 v[186:189], v145 offset:18432
	ds_read_b128 v[190:193], v145 offset:19456
	ds_read_b128 v[194:197], v145 offset:20480
	ds_read_b128 v[198:201], v145 offset:21504
	ds_read_b128 v[202:205], v145 offset:22528
	ds_read_b128 v[212:215], v145 offset:23552
	global_load_lds_dwordx4 v0, s[48:49]
	s_add_i32 m0, s6, 0x2000
	s_add_u32 s6, s48, 0x40000
	s_addc_u32 s7, s49, 0
	s_add_i32 s76, s77, s60
	global_load_lds_dwordx4 v130, s[48:49]
	s_mov_b32 m0, s76
	s_add_u32 s100, s50, s22
	s_addc_u32 s101, s51, s23
	global_load_lds_dwordx4 v0, s[6:7]
	s_add_i32 m0, s76, 0x2000
	s_nop 0
	global_load_lds_dwordx4 v130, s[6:7]
	s_mov_b32 m0, s45
	s_nop 0
	global_load_lds_dwordx4 v134, s[50:51]
	s_mov_b32 m0, s62
	s_nop 0
	global_load_lds_dwordx4 v132, s[50:51]
	s_waitcnt vmcnt(8)
	s_waitcnt lgkmcnt(0)
	s_barrier
	s_setprio 1
	v_mfma_f32_16x16x32_bf16 v[62:65], v[146:149], v[178:181], v[62:65]
	v_mfma_f32_16x16x32_bf16 v[58:61], v[154:157], v[178:181], v[58:61]
	v_mfma_f32_16x16x32_bf16 v[46:49], v[146:149], v[186:189], v[46:49]
	v_mfma_f32_16x16x32_bf16 v[42:45], v[154:157], v[186:189], v[42:45]
	v_mfma_f32_16x16x32_bf16 v[30:33], v[146:149], v[194:197], v[30:33]
	v_mfma_f32_16x16x32_bf16 v[26:29], v[154:157], v[194:197], v[26:29]
	v_mfma_f32_16x16x32_bf16 v[14:17], v[146:149], v[202:205], v[14:17]
	v_mfma_f32_16x16x32_bf16 v[10:13], v[154:157], v[202:205], v[10:13]
	v_mfma_f32_16x16x32_bf16 v[62:65], v[150:153], v[182:185], v[62:65]
	v_mfma_f32_16x16x32_bf16 v[58:61], v[158:161], v[182:185], v[58:61]
	v_mfma_f32_16x16x32_bf16 v[46:49], v[150:153], v[190:193], v[46:49]
	v_mfma_f32_16x16x32_bf16 v[42:45], v[158:161], v[190:193], v[42:45]
	v_mfma_f32_16x16x32_bf16 v[30:33], v[150:153], v[198:201], v[30:33]
	v_mfma_f32_16x16x32_bf16 v[26:29], v[158:161], v[198:201], v[26:29]
	v_mfma_f32_16x16x32_bf16 v[14:17], v[150:153], v[212:215], v[14:17]
	v_mfma_f32_16x16x32_bf16 v[10:13], v[158:161], v[212:215], v[10:13]
	s_setprio 0
	s_setprio 1
	v_mfma_f32_16x16x32_bf16 v[54:57], v[162:165], v[178:181], v[54:57]
	v_mfma_f32_16x16x32_bf16 v[50:53], v[170:173], v[178:181], v[50:53]
	v_mfma_f32_16x16x32_bf16 v[38:41], v[162:165], v[186:189], v[38:41]
	v_mfma_f32_16x16x32_bf16 v[34:37], v[170:173], v[186:189], v[34:37]
	v_mfma_f32_16x16x32_bf16 v[22:25], v[162:165], v[194:197], v[22:25]
	v_mfma_f32_16x16x32_bf16 v[18:21], v[170:173], v[194:197], v[18:21]
	v_mfma_f32_16x16x32_bf16 v[6:9], v[162:165], v[202:205], v[6:9]
	v_mfma_f32_16x16x32_bf16 v[2:5], v[170:173], v[202:205], v[2:5]
	v_mfma_f32_16x16x32_bf16 v[54:57], v[166:169], v[182:185], v[54:57]
	v_mfma_f32_16x16x32_bf16 v[50:53], v[174:177], v[182:185], v[50:53]
	v_mfma_f32_16x16x32_bf16 v[38:41], v[166:169], v[190:193], v[38:41]
	v_mfma_f32_16x16x32_bf16 v[34:37], v[174:177], v[190:193], v[34:37]
	v_mfma_f32_16x16x32_bf16 v[22:25], v[166:169], v[198:201], v[22:25]
	v_mfma_f32_16x16x32_bf16 v[18:21], v[174:177], v[198:201], v[18:21]
	v_mfma_f32_16x16x32_bf16 v[6:9], v[166:169], v[212:215], v[6:9]
	v_mfma_f32_16x16x32_bf16 v[2:5], v[174:177], v[212:215], v[2:5]
	s_setprio 0
	s_barrier
; #define PG8_STAGE(bufoff, gbase, voff) do { _Pragma("unroll") for (int _i = 0; _i < 2; ++_i) \
;         __builtin_amdgcn_global_load_lds((const unsigned*)((const char*)(gbase) + (voff)[_i]), (PG8_LAS unsigned*)(lds + (bufoff) + ldsw + _i * 8192), 16, 0, 0); } while (0)
; #define PG8_LDA(dst, b, h) do { _Pragma("unroll") for (int m = 0; m < 4; ++m) _Pragma("unroll") for (int k = 0; k < 2; ++k) dst[m][k] = *(const PG8_LAS bf16x8*)(lds + PG8_SA(b, h) + aoff + m * 2048 + k * 1024); } while (0)
; #define PG8_LDB(dst, b, h) do { _Pragma("unroll") for (int n = 0; n < 2; ++n) _Pragma("unroll") for (int k = 0; k < 2; ++k) dst[n][k] = *(const PG8_LAS bf16x8*)(lds + PG8_SB(b, h) + boff + n * 2048 + k * 1024); } while (0)
; template <class Epi, class Sched, bool ALIGN_EPI = false, bool SP2 = false>
; __device__ __forceinline__ void gemm_phase(PG8_LAS unsigned char* lds, const Gemm g, const Sched& S, const Epi& E) {
;     ...
;         for (int t = 0; t < unt; t += 2) {
;             const bool last = (t == unt - 2);
;             const char* a1 = cA + (size_t)(t + 1) * kstep;
;             const char* a2 = last ? nA : cA + (size_t)(t + 2) * kstep; const char* b2 = last ? nB : cB + (size_t)(t + 2) * kstep;
;             const char* a3 = a2 + kstep; const char* b3 = b2 + kstep;
;             if (last && has_next) S.a_ready(nxt);
;             if constexpr (SP2) {
;             PG8_LDB(B0, 0, 0); PG8_LDB(B1, 0, 1); PG8_SCHED; PG8_LDA(At, 0, 0); PG8_STAGE(PG8_SA(1, 1), a1 + hstep, voffA);
;             PG8_WAIT_V(8); PG8_WAIT_L(0); PG8_BAR; PG8_MMA(0, 0, At, B0); PG8_MMA(0, 1, At, B1); PG8_BAR; PG8_SCHED;
;             PG8_LDA(At, 0, 1); PG8_STAGE(PG8_SB(0, 0), b2, voffB); PG8_STAGE(PG8_SB(0, 1), b2 + hstep, voffB); PG8_STAGE(PG8_SA(0, 0), a2, voffA);
;             PG8_WAIT_V(8); PG8_WAIT_L(0); PG8_BAR; PG8_MMA(1, 0, At, B0); PG8_MMA(1, 1, At, B1); PG8_BAR; PG8_SCHED;
;             PG8_LDB(B0, 1, 0); PG8_LDB(B1, 1, 1); PG8_SCHED; PG8_LDA(At, 1, 0); PG8_STAGE(PG8_SA(0, 1), a2 + hstep, voffA);
;             PG8_WAIT_V(8); PG8_WAIT_L(0); PG8_BAR; PG8_MMA(0, 0, At, B0); PG8_MMA(0, 1, At, B1); PG8_BAR; PG8_SCHED;
;             PG8_LDA(At, 1, 1); PG8_STAGE(PG8_SB(1, 0), b3, voffB); PG8_STAGE(PG8_SB(1, 1), b3 + hstep, voffB); PG8_STAGE(PG8_SA(1, 0), a3, voffA);
;             PG8_WAIT_V(8); PG8_WAIT_L(0); PG8_BAR; PG8_MMA(1, 0, At, B0); PG8_MMA(1, 1, At, B1); PG8_BAR; PG8_SCHED;
	s_add_i32 s76, 0, 0x18000
	s_add_i32 s77, 0, 0x1c000
	v_add_u32_e32 v158, s76, v143
	v_add_u32_e32 v174, s77, v143
	ds_read_b128 v[146:149], v158
	ds_read_b128 v[150:153], v158 offset:1024
	ds_read_b128 v[154:157], v158 offset:2048
	ds_read_b128 v[158:161], v158 offset:3072
	ds_read_b128 v[162:165], v174
	ds_read_b128 v[166:169], v174 offset:1024
	ds_read_b128 v[170:173], v174 offset:2048
	ds_read_b128 v[174:177], v174 offset:3072
	s_add_u32 s6, s50, 0x40000
	s_addc_u32 s7, s51, 0
	s_mov_b32 m0, s63
	ds_read_b128 v[178:181], v145 offset:32768
	ds_read_b128 v[182:185], v145 offset:33792
	ds_read_b128 v[186:189], v145 offset:34816
	ds_read_b128 v[190:193], v145 offset:35840
	ds_read_b128 v[194:197], v145 offset:36864
	ds_read_b128 v[198:201], v145 offset:37888
	ds_read_b128 v[202:205], v145 offset:38912
	ds_read_b128 v[212:215], v145 offset:39936
	global_load_lds_dwordx4 v134, s[6:7]
	s_mov_b32 m0, s64
	s_nop 0
	global_load_lds_dwordx4 v132, s[6:7]
	s_waitcnt vmcnt(8)
	s_waitcnt lgkmcnt(0)
	s_barrier
	s_setprio 1
	v_mfma_f32_16x16x32_bf16 v[126:129], v[146:149], v[178:181], v[126:129]
	v_mfma_f32_16x16x32_bf16 v[122:125], v[154:157], v[178:181], v[122:125]
	v_mfma_f32_16x16x32_bf16 v[110:113], v[146:149], v[186:189], v[110:113]
	v_mfma_f32_16x16x32_bf16 v[106:109], v[154:157], v[186:189], v[106:109]
	v_mfma_f32_16x16x32_bf16 v[94:97], v[146:149], v[194:197], v[94:97]
	v_mfma_f32_16x16x32_bf16 v[90:93], v[154:157], v[194:197], v[90:93]
	v_mfma_f32_16x16x32_bf16 v[78:81], v[146:149], v[202:205], v[78:81]
	v_mfma_f32_16x16x32_bf16 v[74:77], v[154:157], v[202:205], v[74:77]
	v_mfma_f32_16x16x32_bf16 v[126:129], v[150:153], v[182:185], v[126:129]
	v_mfma_f32_16x16x32_bf16 v[122:125], v[158:161], v[182:185], v[122:125]
	v_mfma_f32_16x16x32_bf16 v[110:113], v[150:153], v[190:193], v[110:113]
	v_mfma_f32_16x16x32_bf16 v[106:109], v[158:161], v[190:193], v[106:109]
	v_mfma_f32_16x16x32_bf16 v[94:97], v[150:153], v[198:201], v[94:97]
	v_mfma_f32_16x16x32_bf16 v[90:93], v[158:161], v[198:201], v[90:93]
	v_mfma_f32_16x16x32_bf16 v[78:81], v[150:153], v[212:215], v[78:81]
	v_mfma_f32_16x16x32_bf16 v[74:77], v[158:161], v[212:215], v[74:77]
	s_setprio 0
	s_setprio 1
	v_mfma_f32_16x16x32_bf16 v[118:121], v[162:165], v[178:181], v[118:121]
	v_mfma_f32_16x16x32_bf16 v[114:117], v[170:173], v[178:181], v[114:117]
	v_mfma_f32_16x16x32_bf16 v[102:105], v[162:165], v[186:189], v[102:105]
	v_mfma_f32_16x16x32_bf16 v[98:101], v[170:173], v[186:189], v[98:101]
	v_mfma_f32_16x16x32_bf16 v[86:89], v[162:165], v[194:197], v[86:89]
	v_mfma_f32_16x16x32_bf16 v[82:85], v[170:173], v[194:197], v[82:85]
	v_mfma_f32_16x16x32_bf16 v[70:73], v[162:165], v[202:205], v[70:73]
	v_mfma_f32_16x16x32_bf16 v[66:69], v[170:173], v[202:205], v[66:69]
	v_mfma_f32_16x16x32_bf16 v[118:121], v[166:169], v[182:185], v[118:121]
	v_mfma_f32_16x16x32_bf16 v[114:117], v[174:177], v[182:185], v[114:117]
	v_mfma_f32_16x16x32_bf16 v[102:105], v[166:169], v[190:193], v[102:105]
	v_mfma_f32_16x16x32_bf16 v[98:101], v[174:177], v[190:193], v[98:101]
	v_mfma_f32_16x16x32_bf16 v[86:89], v[166:169], v[198:201], v[86:89]
	v_mfma_f32_16x16x32_bf16 v[82:85], v[174:177], v[198:201], v[82:85]
	v_mfma_f32_16x16x32_bf16 v[70:73], v[166:169], v[212:215], v[70:73]
	v_mfma_f32_16x16x32_bf16 v[66:69], v[174:177], v[212:215], v[66:69]
	s_setprio 0
	s_barrier
	s_add_i32 s6, s76, s60
	s_mov_b32 m0, s6
	ds_read_b128 v[178:181], v145 offset:49152
	ds_read_b128 v[182:185], v145 offset:50176
	ds_read_b128 v[186:189], v145 offset:51200
	ds_read_b128 v[190:193], v145 offset:52224
	ds_read_b128 v[194:197], v145 offset:53248
	ds_read_b128 v[198:201], v145 offset:54272
	ds_read_b128 v[202:205], v145 offset:55296
	ds_read_b128 v[212:215], v145 offset:56320
	global_load_lds_dwordx4 v0, s[98:99]
	s_add_i32 m0, s6, 0x2000
	s_add_u32 s6, s48, 0x40080
	s_addc_u32 s7, s49, 0
	s_add_i32 s48, s77, s60
	global_load_lds_dwordx4 v130, s[98:99]
	s_mov_b32 m0, s48
	s_nop 0
	global_load_lds_dwordx4 v0, s[6:7]
	s_add_i32 m0, s48, 0x2000
	s_nop 0
	global_load_lds_dwordx4 v130, s[6:7]
	s_mov_b32 m0, s65
	s_nop 0
	global_load_lds_dwordx4 v134, s[100:101]
	s_mov_b32 m0, s66
	s_nop 0
	global_load_lds_dwordx4 v132, s[100:101]
	s_waitcnt vmcnt(8)
	s_waitcnt lgkmcnt(0)
	s_barrier
	s_setprio 1
	v_mfma_f32_16x16x32_bf16 v[62:65], v[146:149], v[178:181], v[62:65]
	v_mfma_f32_16x16x32_bf16 v[58:61], v[154:157], v[178:181], v[58:61]
	v_mfma_f32_16x16x32_bf16 v[46:49], v[146:149], v[186:189], v[46:49]
	v_mfma_f32_16x16x32_bf16 v[42:45], v[154:157], v[186:189], v[42:45]
	v_mfma_f32_16x16x32_bf16 v[30:33], v[146:149], v[194:197], v[30:33]
	v_mfma_f32_16x16x32_bf16 v[26:29], v[154:157], v[194:197], v[26:29]
	v_mfma_f32_16x16x32_bf16 v[14:17], v[146:149], v[202:205], v[14:17]
	v_mfma_f32_16x16x32_bf16 v[10:13], v[154:157], v[202:205], v[10:13]
	v_mfma_f32_16x16x32_bf16 v[62:65], v[150:153], v[182:185], v[62:65]
	v_mfma_f32_16x16x32_bf16 v[58:61], v[158:161], v[182:185], v[58:61]
	v_mfma_f32_16x16x32_bf16 v[46:49], v[150:153], v[190:193], v[46:49]
	v_mfma_f32_16x16x32_bf16 v[42:45], v[158:161], v[190:193], v[42:45]
	v_mfma_f32_16x16x32_bf16 v[30:33], v[150:153], v[198:201], v[30:33]
	v_mfma_f32_16x16x32_bf16 v[26:29], v[158:161], v[198:201], v[26:29]
	v_mfma_f32_16x16x32_bf16 v[14:17], v[150:153], v[212:215], v[14:17]
	v_mfma_f32_16x16x32_bf16 v[10:13], v[158:161], v[212:215], v[10:13]
	s_setprio 0
	s_setprio 1
	v_mfma_f32_16x16x32_bf16 v[54:57], v[162:165], v[178:181], v[54:57]
	v_mfma_f32_16x16x32_bf16 v[50:53], v[170:173], v[178:181], v[50:53]
	v_mfma_f32_16x16x32_bf16 v[38:41], v[162:165], v[186:189], v[38:41]
	v_mfma_f32_16x16x32_bf16 v[34:37], v[170:173], v[186:189], v[34:37]
	v_mfma_f32_16x16x32_bf16 v[22:25], v[162:165], v[194:197], v[22:25]
	v_mfma_f32_16x16x32_bf16 v[18:21], v[170:173], v[194:197], v[18:21]
	v_mfma_f32_16x16x32_bf16 v[6:9], v[162:165], v[202:205], v[6:9]
	v_mfma_f32_16x16x32_bf16 v[2:5], v[170:173], v[202:205], v[2:5]
	v_mfma_f32_16x16x32_bf16 v[54:57], v[166:169], v[182:185], v[54:57]
	v_mfma_f32_16x16x32_bf16 v[50:53], v[174:177], v[182:185], v[50:53]
	v_mfma_f32_16x16x32_bf16 v[38:41], v[166:169], v[190:193], v[38:41]
	v_mfma_f32_16x16x32_bf16 v[34:37], v[174:177], v[190:193], v[34:37]
	v_mfma_f32_16x16x32_bf16 v[22:25], v[166:169], v[198:201], v[22:25]
	v_mfma_f32_16x16x32_bf16 v[18:21], v[174:177], v[198:201], v[18:21]
	v_mfma_f32_16x16x32_bf16 v[6:9], v[166:169], v[212:215], v[6:9]
	v_mfma_f32_16x16x32_bf16 v[2:5], v[174:177], v[212:215], v[2:5]
	s_setprio 0
	s_barrier
	s_add_i32 s71, s71, 2
	s_add_u32 s46, s46, 0x100
	s_addc_u32 s47, s47, 0
	s_add_u32 s69, s69, 0x100
	s_addc_u32 s70, s70, 0
	s_cmp_gt_u32 s71, 13
	s_cbranch_scc0 .LBB0_1026
	s_and_b64 vcc, exec, s[26:27]
	s_cbranch_vccz .LBB0_1029
	s_barrier

; #define PG8_STAGE(bufoff, gbase, voff) do { _Pragma("unroll") for (int _i = 0; _i < 2; ++_i) \
;         __builtin_amdgcn_global_load_lds((const unsigned*)((const char*)(gbase) + (voff)[_i]), (PG8_LAS unsigned*)(lds + (bufoff) + ldsw + _i * 8192), 16, 0, 0); } while (0)
; #define PG8_LDA(dst, b, h) do { _Pragma("unroll") for (int m = 0; m < 4; ++m) _Pragma("unroll") for (int k = 0; k < 2; ++k) dst[m][k] = *(const PG8_LAS bf16x8*)(lds + PG8_SA(b, h) + aoff + m * 2048 + k * 1024); } while (0)
; #define PG8_LDB(dst, b, h) do { _Pragma("unroll") for (int n = 0; n < 2; ++n) _Pragma("unroll") for (int k = 0; k < 2; ++k) dst[n][k] = *(const PG8_LAS bf16x8*)(lds + PG8_SB(b, h) + boff + n * 2048 + k * 1024); } while (0)
; #define PG8_WAIT_V(n) asm volatile("s_waitcnt vmcnt(" #n ")" ::: "memory")
; #define PG8_WAIT_L(n) asm volatile("s_waitcnt lgkmcnt(" #n ")" ::: "memory")
; template <class Epi, class Sched, bool ALIGN_EPI = false, bool SP2 = false>
; __device__ __forceinline__ void gemm_phase(PG8_LAS unsigned char* lds, const Gemm g, const Sched& S, const Epi& E) {
;     ...
;     for (;;) {
;         const bool has_next = S.next(ui + 1, nxt);
;         const char* nA = has_next ? (const char*)g.A + (size_t)nxt.pm * tstep + (size_t)nxt.k0 * 2 : cA; const char* nB = has_next ? (const char*)g.Bt + (size_t)nxt.pn * tstep + (size_t)nxt.k0 * 2 : cB;
;         const int unt = cur.nt ? cur.nt : nt;
;         for (int t = 0; t < unt; t += 2) {
;             const bool last = (t == unt - 2);
;             const char* a1 = cA + (size_t)(t + 1) * kstep;
;             const char* a2 = last ? nA : cA + (size_t)(t + 2) * kstep; const char* b2 = last ? nB : cB + (size_t)(t + 2) * kstep;
;             const char* a3 = a2 + kstep; const char* b3 = b2 + kstep;
;             if (last && has_next) S.a_ready(nxt);
;             if constexpr (SP2) {
;             PG8_LDB(B0, 0, 0); PG8_LDB(B1, 0, 1); PG8_SCHED; PG8_LDA(At, 0, 0); PG8_STAGE(PG8_SA(1, 1), a1 + hstep, voffA);
;             PG8_WAIT_V(8); PG8_WAIT_L(0); PG8_BAR; PG8_MMA(0, 0, At, B0); PG8_MMA(0, 1, At, B1); PG8_BAR; PG8_SCHED;
;             PG8_LDA(At, 0, 1); PG8_STAGE(PG8_SB(0, 0), b2, voffB); PG8_STAGE(PG8_SB(0, 1), b2 + hstep, voffB); PG8_STAGE(PG8_SA(0, 0), a2, voffA);
;             PG8_WAIT_V(8); PG8_WAIT_L(0); PG8_BAR; PG8_MMA(1, 0, At, B0); PG8_MMA(1, 1, At, B1); PG8_BAR; PG8_SCHED;
.LBB0_1122:
	s_add_i32 s51, s49, 2
	s_add_u32 s40, s34, 0x100
	s_addc_u32 s41, s35, 0
	s_add_i32 s6, 0, 0x10000
	s_cmp_eq_u32 s5, s49
	s_cselect_b32 s61, s55, s41
	s_cselect_b32 s60, s54, s40
	s_cselect_b32 s59, s57, s27
	s_cselect_b32 s58, s56, s25
	s_add_i32 s49, 0, 0x14000
	s_waitcnt vmcnt(0)
	v_add_u32_e32 v78, s6, v163
	v_add_u32_e32 v160, s49, v163
	ds_read_b128 v[54:57], v78
	ds_read_b128 v[62:65], v78 offset:1024
	ds_read_b128 v[70:73], v78 offset:2048
	ds_read_b128 v[78:81], v78 offset:3072
	ds_read_b128 v[152:155], v160
	ds_read_b128 v[156:159], v160 offset:1024
	ds_read_b128 v[166:169], v160 offset:2048
	ds_read_b128 v[170:173], v160 offset:3072
	s_add_i32 m0, s43, 0xc000
	ds_read_b128 v[174:177], v165
	ds_read_b128 v[178:181], v165 offset:1024
	ds_read_b128 v[182:185], v165 offset:2048
	ds_read_b128 v[186:189], v165 offset:3072
	ds_read_b128 v[190:193], v165 offset:4096
	ds_read_b128 v[194:197], v165 offset:5120
	ds_read_b128 v[198:201], v165 offset:6144
	ds_read_b128 v[202:205], v165 offset:7168
	global_load_lds_dwordx4 v148, s[34:35]
	s_add_i32 m0, s43, 0xe000
	s_nop 0
	global_load_lds_dwordx4 v150, s[34:35]
	s_waitcnt vmcnt(8)
	s_waitcnt lgkmcnt(0)
	s_barrier
	s_setprio 1
	v_mfma_f32_16x16x32_bf16 v[142:145], v[54:57], v[174:177], v[142:145]
	v_mfma_f32_16x16x32_bf16 v[138:141], v[70:73], v[174:177], v[138:141]
	v_mfma_f32_16x16x32_bf16 v[126:129], v[54:57], v[182:185], v[126:129]
	v_mfma_f32_16x16x32_bf16 v[122:125], v[70:73], v[182:185], v[122:125]
	v_mfma_f32_16x16x32_bf16 v[110:113], v[54:57], v[190:193], v[110:113]
	v_mfma_f32_16x16x32_bf16 v[106:109], v[70:73], v[190:193], v[106:109]
	v_mfma_f32_16x16x32_bf16 v[94:97], v[54:57], v[198:201], v[94:97]
	v_mfma_f32_16x16x32_bf16 v[90:93], v[70:73], v[198:201], v[90:93]
	v_mfma_f32_16x16x32_bf16 v[142:145], v[62:65], v[178:181], v[142:145]
	v_mfma_f32_16x16x32_bf16 v[138:141], v[78:81], v[178:181], v[138:141]
	v_mfma_f32_16x16x32_bf16 v[126:129], v[62:65], v[186:189], v[126:129]
	v_mfma_f32_16x16x32_bf16 v[122:125], v[78:81], v[186:189], v[122:125]
	v_mfma_f32_16x16x32_bf16 v[110:113], v[62:65], v[194:197], v[110:113]
	v_mfma_f32_16x16x32_bf16 v[106:109], v[78:81], v[194:197], v[106:109]
	v_mfma_f32_16x16x32_bf16 v[94:97], v[62:65], v[202:205], v[94:97]
	v_mfma_f32_16x16x32_bf16 v[90:93], v[78:81], v[202:205], v[90:93]
	s_setprio 0
	s_setprio 1
	v_mfma_f32_16x16x32_bf16 v[134:137], v[152:155], v[174:177], v[134:137]
	v_mfma_f32_16x16x32_bf16 v[130:133], v[166:169], v[174:177], v[130:133]
	v_mfma_f32_16x16x32_bf16 v[118:121], v[152:155], v[182:185], v[118:121]
	v_mfma_f32_16x16x32_bf16 v[114:117], v[166:169], v[182:185], v[114:117]
	v_mfma_f32_16x16x32_bf16 v[102:105], v[152:155], v[190:193], v[102:105]
	v_mfma_f32_16x16x32_bf16 v[98:101], v[166:169], v[190:193], v[98:101]
	v_mfma_f32_16x16x32_bf16 v[86:89], v[152:155], v[198:201], v[86:89]
	v_mfma_f32_16x16x32_bf16 v[82:85], v[166:169], v[198:201], v[82:85]
	v_mfma_f32_16x16x32_bf16 v[134:137], v[156:159], v[178:181], v[134:137]
	v_mfma_f32_16x16x32_bf16 v[130:133], v[170:173], v[178:181], v[130:133]
	v_mfma_f32_16x16x32_bf16 v[118:121], v[156:159], v[186:189], v[118:121]
	v_mfma_f32_16x16x32_bf16 v[114:117], v[170:173], v[186:189], v[114:117]
	v_mfma_f32_16x16x32_bf16 v[102:105], v[156:159], v[194:197], v[102:105]
	v_mfma_f32_16x16x32_bf16 v[98:101], v[170:173], v[194:197], v[98:101]
	v_mfma_f32_16x16x32_bf16 v[86:89], v[156:159], v[202:205], v[86:89]
	v_mfma_f32_16x16x32_bf16 v[82:85], v[170:173], v[202:205], v[82:85]
	s_setprio 0
	s_barrier
	s_add_i32 s6, s6, s67
	s_add_u32 s98, s58, s22
	s_addc_u32 s99, s59, s23
	s_mov_b32 m0, s6
	ds_read_b128 v[174:177], v165 offset:16384
	ds_read_b128 v[178:181], v165 offset:17408
	ds_read_b128 v[182:185], v165 offset:18432
	ds_read_b128 v[186:189], v165 offset:19456
	ds_read_b128 v[190:193], v165 offset:20480
	ds_read_b128 v[194:197], v165 offset:21504
	ds_read_b128 v[198:201], v165 offset:22528
	ds_read_b128 v[202:205], v165 offset:23552
	global_load_lds_dwordx4 v0, s[58:59]
	s_add_i32 m0, s6, 0x2000
	s_add_u32 s6, s58, 0x100000
	s_addc_u32 s7, s59, 0
	s_add_i32 s34, s49, s67
	global_load_lds_dwordx4 v146, s[58:59]
	s_mov_b32 m0, s34
	s_add_u32 s100, s60, s22
	s_addc_u32 s101, s61, s23
	global_load_lds_dwordx4 v0, s[6:7]
	s_add_i32 m0, s34, 0x2000
	s_nop 0
	global_load_lds_dwordx4 v146, s[6:7]
	s_mov_b32 m0, s43
	s_nop 0
	global_load_lds_dwordx4 v0, s[60:61]
	s_mov_b32 m0, s76
	s_nop 0
	global_load_lds_dwordx4 v146, s[60:61]
	s_waitcnt vmcnt(8)
	s_waitcnt lgkmcnt(0)
	s_barrier
	s_setprio 1
	v_mfma_f32_16x16x32_bf16 v[74:77], v[54:57], v[174:177], v[74:77]
	v_mfma_f32_16x16x32_bf16 v[66:69], v[70:73], v[174:177], v[66:69]
	v_mfma_f32_16x16x32_bf16 v[46:49], v[54:57], v[182:185], v[46:49]
	v_mfma_f32_16x16x32_bf16 v[42:45], v[70:73], v[182:185], v[42:45]
	v_mfma_f32_16x16x32_bf16 v[30:33], v[54:57], v[190:193], v[30:33]
	v_mfma_f32_16x16x32_bf16 v[26:29], v[70:73], v[190:193], v[26:29]
	v_mfma_f32_16x16x32_bf16 v[14:17], v[54:57], v[198:201], v[14:17]
	v_mfma_f32_16x16x32_bf16 v[10:13], v[70:73], v[198:201], v[10:13]
	v_mfma_f32_16x16x32_bf16 v[74:77], v[62:65], v[178:181], v[74:77]
	v_mfma_f32_16x16x32_bf16 v[66:69], v[78:81], v[178:181], v[66:69]
	v_mfma_f32_16x16x32_bf16 v[46:49], v[62:65], v[186:189], v[46:49]
	v_mfma_f32_16x16x32_bf16 v[42:45], v[78:81], v[186:189], v[42:45]
	v_mfma_f32_16x16x32_bf16 v[30:33], v[62:65], v[194:197], v[30:33]
	v_mfma_f32_16x16x32_bf16 v[26:29], v[78:81], v[194:197], v[26:29]
	v_mfma_f32_16x16x32_bf16 v[14:17], v[62:65], v[202:205], v[14:17]
	v_mfma_f32_16x16x32_bf16 v[10:13], v[78:81], v[202:205], v[10:13]
	s_setprio 0
	s_setprio 1
	v_mfma_f32_16x16x32_bf16 v[50:53], v[166:169], v[174:177], v[50:53]
	v_mfma_f32_16x16x32_bf16 v[38:41], v[152:155], v[182:185], v[38:41]
	v_mfma_f32_16x16x32_bf16 v[34:37], v[166:169], v[182:185], v[34:37]
	v_mfma_f32_16x16x32_bf16 v[22:25], v[152:155], v[190:193], v[22:25]
	v_mfma_f32_16x16x32_bf16 v[18:21], v[166:169], v[190:193], v[18:21]
	v_mfma_f32_16x16x32_bf16 v[6:9], v[152:155], v[198:201], v[6:9]
	v_mfma_f32_16x16x32_bf16 v[2:5], v[166:169], v[198:201], v[2:5]
	v_mfma_f32_16x16x32_bf16 v[54:57], v[152:155], v[174:177], v[58:61]
	v_mfma_f32_16x16x32_bf16 v[50:53], v[170:173], v[178:181], v[50:53]
	v_mfma_f32_16x16x32_bf16 v[38:41], v[156:159], v[186:189], v[38:41]
	v_mfma_f32_16x16x32_bf16 v[34:37], v[170:173], v[186:189], v[34:37]
	v_mfma_f32_16x16x32_bf16 v[22:25], v[156:159], v[194:197], v[22:25]
	v_mfma_f32_16x16x32_bf16 v[18:21], v[170:173], v[194:197], v[18:21]
	v_mfma_f32_16x16x32_bf16 v[6:9], v[156:159], v[202:205], v[6:9]
	v_mfma_f32_16x16x32_bf16 v[2:5], v[170:173], v[202:205], v[2:5]
	v_mfma_f32_16x16x32_bf16 v[54:57], v[156:159], v[178:181], v[54:57]
	s_setprio 0
	s_barrier
; #define PG8_STAGE(bufoff, gbase, voff) do { _Pragma("unroll") for (int _i = 0; _i < 2; ++_i) \
;         __builtin_amdgcn_global_load_lds((const unsigned*)((const char*)(gbase) + (voff)[_i]), (PG8_LAS unsigned*)(lds + (bufoff) + ldsw + _i * 8192), 16, 0, 0); } while (0)
; #define PG8_LDA(dst, b, h) do { _Pragma("unroll") for (int m = 0; m < 4; ++m) _Pragma("unroll") for (int k = 0; k < 2; ++k) dst[m][k] = *(const PG8_LAS bf16x8*)(lds + PG8_SA(b, h) + aoff + m * 2048 + k * 1024); } while (0)
; #define PG8_LDB(dst, b, h) do { _Pragma("unroll") for (int n = 0; n < 2; ++n) _Pragma("unroll") for (int k = 0; k < 2; ++k) dst[n][k] = *(const PG8_LAS bf16x8*)(lds + PG8_SB(b, h) + boff + n * 2048 + k * 1024); } while (0)
; template <class Epi, class Sched, bool ALIGN_EPI = false, bool SP2 = false>
; __device__ __forceinline__ void gemm_phase(PG8_LAS unsigned char* lds, const Gemm g, const Sched& S, const Epi& E) {
;     ...
;         for (int t = 0; t < unt; t += 2) {
;             const bool last = (t == unt - 2);
;             const char* a1 = cA + (size_t)(t + 1) * kstep;
;             const char* a2 = last ? nA : cA + (size_t)(t + 2) * kstep; const char* b2 = last ? nB : cB + (size_t)(t + 2) * kstep;
;             const char* a3 = a2 + kstep; const char* b3 = b2 + kstep;
;             if (last && has_next) S.a_ready(nxt);
;             if constexpr (SP2) {
;             PG8_LDB(B0, 0, 0); PG8_LDB(B1, 0, 1); PG8_SCHED; PG8_LDA(At, 0, 0); PG8_STAGE(PG8_SA(1, 1), a1 + hstep, voffA);
;             PG8_WAIT_V(8); PG8_WAIT_L(0); PG8_BAR; PG8_MMA(0, 0, At, B0); PG8_MMA(0, 1, At, B1); PG8_BAR; PG8_SCHED;
;             PG8_LDA(At, 0, 1); PG8_STAGE(PG8_SB(0, 0), b2, voffB); PG8_STAGE(PG8_SB(0, 1), b2 + hstep, voffB); PG8_STAGE(PG8_SA(0, 0), a2, voffA);
;             PG8_WAIT_V(8); PG8_WAIT_L(0); PG8_BAR; PG8_MMA(1, 0, At, B0); PG8_MMA(1, 1, At, B1); PG8_BAR; PG8_SCHED;
;             PG8_LDB(B0, 1, 0); PG8_LDB(B1, 1, 1); PG8_SCHED; PG8_LDA(At, 1, 0); PG8_STAGE(PG8_SA(0, 1), a2 + hstep, voffA);
;             PG8_WAIT_V(8); PG8_WAIT_L(0); PG8_BAR; PG8_MMA(0, 0, At, B0); PG8_MMA(0, 1, At, B1); PG8_BAR; PG8_SCHED;
;             PG8_LDA(At, 1, 1); PG8_STAGE(PG8_SB(1, 0), b3, voffB); PG8_STAGE(PG8_SB(1, 1), b3 + hstep, voffB); PG8_STAGE(PG8_SA(1, 0), a3, voffA);
;             PG8_WAIT_V(8); PG8_WAIT_L(0); PG8_BAR; PG8_MMA(1, 0, At, B0); PG8_MMA(1, 1, At, B1); PG8_BAR; PG8_SCHED;
	s_add_i32 s34, 0, 0x18000
	s_add_i32 s35, 0, 0x1c000
	v_add_u32_e32 v78, s34, v163
	v_add_u32_e32 v170, s35, v163
	ds_read_b128 v[58:61], v78
	ds_read_b128 v[62:65], v78 offset:1024
	ds_read_b128 v[70:73], v78 offset:2048
	ds_read_b128 v[78:81], v78 offset:3072
	ds_read_b128 v[152:155], v170
	ds_read_b128 v[156:159], v170 offset:1024
	ds_read_b128 v[166:169], v170 offset:2048
	ds_read_b128 v[170:173], v170 offset:3072
	s_add_u32 s6, s60, 0x100000
	s_addc_u32 s7, s61, 0
	s_mov_b32 m0, s77
	ds_read_b128 v[174:177], v165 offset:32768
	ds_read_b128 v[178:181], v165 offset:33792
	ds_read_b128 v[182:185], v165 offset:34816
	ds_read_b128 v[186:189], v165 offset:35840
	ds_read_b128 v[190:193], v165 offset:36864
	ds_read_b128 v[194:197], v165 offset:37888
	ds_read_b128 v[198:201], v165 offset:38912
	ds_read_b128 v[202:205], v165 offset:39936
	global_load_lds_dwordx4 v0, s[6:7]
	s_mov_b32 m0, s82
	s_nop 0
	global_load_lds_dwordx4 v146, s[6:7]
	s_waitcnt vmcnt(8)
	s_waitcnt lgkmcnt(0)
	s_barrier
	s_setprio 1
	v_mfma_f32_16x16x32_bf16 v[142:145], v[58:61], v[174:177], v[142:145]
	v_mfma_f32_16x16x32_bf16 v[138:141], v[70:73], v[174:177], v[138:141]
	v_mfma_f32_16x16x32_bf16 v[126:129], v[58:61], v[182:185], v[126:129]
	v_mfma_f32_16x16x32_bf16 v[122:125], v[70:73], v[182:185], v[122:125]
	v_mfma_f32_16x16x32_bf16 v[110:113], v[58:61], v[190:193], v[110:113]
	v_mfma_f32_16x16x32_bf16 v[106:109], v[70:73], v[190:193], v[106:109]
	v_mfma_f32_16x16x32_bf16 v[94:97], v[58:61], v[198:201], v[94:97]
	v_mfma_f32_16x16x32_bf16 v[90:93], v[70:73], v[198:201], v[90:93]
	v_mfma_f32_16x16x32_bf16 v[142:145], v[62:65], v[178:181], v[142:145]
	v_mfma_f32_16x16x32_bf16 v[138:141], v[78:81], v[178:181], v[138:141]
	v_mfma_f32_16x16x32_bf16 v[126:129], v[62:65], v[186:189], v[126:129]
	v_mfma_f32_16x16x32_bf16 v[122:125], v[78:81], v[186:189], v[122:125]
	v_mfma_f32_16x16x32_bf16 v[110:113], v[62:65], v[194:197], v[110:113]
	v_mfma_f32_16x16x32_bf16 v[106:109], v[78:81], v[194:197], v[106:109]
	v_mfma_f32_16x16x32_bf16 v[94:97], v[62:65], v[202:205], v[94:97]
	v_mfma_f32_16x16x32_bf16 v[90:93], v[78:81], v[202:205], v[90:93]
	s_setprio 0
	s_setprio 1
	v_mfma_f32_16x16x32_bf16 v[134:137], v[152:155], v[174:177], v[134:137]
	v_mfma_f32_16x16x32_bf16 v[130:133], v[166:169], v[174:177], v[130:133]
	v_mfma_f32_16x16x32_bf16 v[118:121], v[152:155], v[182:185], v[118:121]
	v_mfma_f32_16x16x32_bf16 v[114:117], v[166:169], v[182:185], v[114:117]
	v_mfma_f32_16x16x32_bf16 v[102:105], v[152:155], v[190:193], v[102:105]
	v_mfma_f32_16x16x32_bf16 v[98:101], v[166:169], v[190:193], v[98:101]
	v_mfma_f32_16x16x32_bf16 v[86:89], v[152:155], v[198:201], v[86:89]
	v_mfma_f32_16x16x32_bf16 v[82:85], v[166:169], v[198:201], v[82:85]
	v_mfma_f32_16x16x32_bf16 v[134:137], v[156:159], v[178:181], v[134:137]
	v_mfma_f32_16x16x32_bf16 v[130:133], v[170:173], v[178:181], v[130:133]
	v_mfma_f32_16x16x32_bf16 v[118:121], v[156:159], v[186:189], v[118:121]
	v_mfma_f32_16x16x32_bf16 v[114:117], v[170:173], v[186:189], v[114:117]
	v_mfma_f32_16x16x32_bf16 v[102:105], v[156:159], v[194:197], v[102:105]
	v_mfma_f32_16x16x32_bf16 v[98:101], v[170:173], v[194:197], v[98:101]
	v_mfma_f32_16x16x32_bf16 v[86:89], v[156:159], v[202:205], v[86:89]
	v_mfma_f32_16x16x32_bf16 v[82:85], v[170:173], v[202:205], v[82:85]
	s_setprio 0
	s_barrier
	s_add_i32 s6, s34, s67
	s_mov_b32 m0, s6
	ds_read_b128 v[174:177], v165 offset:49152
	ds_read_b128 v[178:181], v165 offset:50176
	ds_read_b128 v[182:185], v165 offset:51200
	ds_read_b128 v[186:189], v165 offset:52224
	ds_read_b128 v[190:193], v165 offset:53248
	ds_read_b128 v[194:197], v165 offset:54272
	ds_read_b128 v[198:201], v165 offset:55296
	ds_read_b128 v[202:205], v165 offset:56320
	global_load_lds_dwordx4 v0, s[98:99]
	s_add_i32 m0, s6, 0x2000
	s_add_u32 s6, s58, 0x100080
	s_addc_u32 s7, s59, 0
	s_add_i32 s34, s35, s67
	global_load_lds_dwordx4 v146, s[98:99]
	s_mov_b32 m0, s34
	s_nop 0
	global_load_lds_dwordx4 v0, s[6:7]
	s_add_i32 m0, s34, 0x2000
	s_nop 0
	global_load_lds_dwordx4 v146, s[6:7]
	s_mov_b32 m0, s87
	s_nop 0
	global_load_lds_dwordx4 v0, s[100:101]
	s_mov_b32 m0, s92
	s_nop 0
	global_load_lds_dwordx4 v146, s[100:101]
	s_waitcnt vmcnt(8)
	s_waitcnt lgkmcnt(0)
	s_barrier
	s_setprio 1
	v_mfma_f32_16x16x32_bf16 v[74:77], v[58:61], v[174:177], v[74:77]
	v_mfma_f32_16x16x32_bf16 v[66:69], v[70:73], v[174:177], v[66:69]
	v_mfma_f32_16x16x32_bf16 v[46:49], v[58:61], v[182:185], v[46:49]
	v_mfma_f32_16x16x32_bf16 v[42:45], v[70:73], v[182:185], v[42:45]
	v_mfma_f32_16x16x32_bf16 v[30:33], v[58:61], v[190:193], v[30:33]
	v_mfma_f32_16x16x32_bf16 v[26:29], v[70:73], v[190:193], v[26:29]
	v_mfma_f32_16x16x32_bf16 v[14:17], v[58:61], v[198:201], v[14:17]
	v_mfma_f32_16x16x32_bf16 v[10:13], v[70:73], v[198:201], v[10:13]
	v_mfma_f32_16x16x32_bf16 v[74:77], v[62:65], v[178:181], v[74:77]
	v_mfma_f32_16x16x32_bf16 v[66:69], v[78:81], v[178:181], v[66:69]
	v_mfma_f32_16x16x32_bf16 v[46:49], v[62:65], v[186:189], v[46:49]
	v_mfma_f32_16x16x32_bf16 v[42:45], v[78:81], v[186:189], v[42:45]
	v_mfma_f32_16x16x32_bf16 v[30:33], v[62:65], v[194:197], v[30:33]
	v_mfma_f32_16x16x32_bf16 v[26:29], v[78:81], v[194:197], v[26:29]
	v_mfma_f32_16x16x32_bf16 v[14:17], v[62:65], v[202:205], v[14:17]
	v_mfma_f32_16x16x32_bf16 v[10:13], v[78:81], v[202:205], v[10:13]
	s_setprio 0
	s_setprio 1
	v_mfma_f32_16x16x32_bf16 v[54:57], v[152:155], v[174:177], v[54:57]
	v_mfma_f32_16x16x32_bf16 v[50:53], v[166:169], v[174:177], v[50:53]
	v_mfma_f32_16x16x32_bf16 v[38:41], v[152:155], v[182:185], v[38:41]
	v_mfma_f32_16x16x32_bf16 v[34:37], v[166:169], v[182:185], v[34:37]
	v_mfma_f32_16x16x32_bf16 v[22:25], v[152:155], v[190:193], v[22:25]
	v_mfma_f32_16x16x32_bf16 v[18:21], v[166:169], v[190:193], v[18:21]
	v_mfma_f32_16x16x32_bf16 v[6:9], v[152:155], v[198:201], v[6:9]
	v_mfma_f32_16x16x32_bf16 v[2:5], v[166:169], v[198:201], v[2:5]
	v_mfma_f32_16x16x32_bf16 v[58:61], v[156:159], v[178:181], v[54:57]
	v_mfma_f32_16x16x32_bf16 v[50:53], v[170:173], v[178:181], v[50:53]
	v_mfma_f32_16x16x32_bf16 v[38:41], v[156:159], v[186:189], v[38:41]
	v_mfma_f32_16x16x32_bf16 v[34:37], v[170:173], v[186:189], v[34:37]
	v_mfma_f32_16x16x32_bf16 v[22:25], v[156:159], v[194:197], v[22:25]
	v_mfma_f32_16x16x32_bf16 v[18:21], v[170:173], v[194:197], v[18:21]
	v_mfma_f32_16x16x32_bf16 v[6:9], v[156:159], v[202:205], v[6:9]
	v_mfma_f32_16x16x32_bf16 v[2:5], v[170:173], v[202:205], v[2:5]
	s_setprio 0
	s_barrier
	s_add_u32 s25, s25, 0x100
	s_addc_u32 s27, s27, 0
	s_cmp_ge_i32 s51, s4
	s_mov_b64 s[34:35], s[40:41]
	s_mov_b32 s49, s51
	s_cbranch_scc0 .LBB0_1122
	s_and_b64 vcc, exec, s[46:47]
	s_cbranch_vccz .LBB0_1125
